# fused two RMSNorm phases into producer residual epilogues (bf16 x*g + row sum-of-squares partials) with rstd applied in consumer GEMM epilogues; two grid barriers per group removed
# speedup vs baseline: 1.0574x; 1.0108x over previous
.LBB0_1267:
	v_lshrrev_b32_e32 v210, 1, v166
	v_and_b32_e32 v210, 0x80, v210
	v_and_b32_e32 v211, 15, v166
	v_or_b32_e32 v210, v210, v211
	v_and_b32_e32 v211, 0xc0, v166
	v_and_b32_e32 v212, 16, v166
	v_lshrrev_b32_e32 v213, 2, v166
	v_and_b32_e32 v213, 8, v213
	v_or_b32_e32 v212, v212, v213
	v_lshlrev_b32_e32 v213, 10, v210
	v_add3_u32 v213, v213, v211, v212
	v_lshlrev_b32_e32 v213, 1, v213
	v_lshl_add_u32 v213, s0, 19, v213
	v_lshl_add_u32 v213, s24, 9, v213
	v_lshlrev_b32_e32 v214, 6, v210
	v_lshrrev_b32_e32 v215, 4, v211
	v_add_u32_e32 v214, v214, v215
	v_lshl_add_u32 v214, s0, 14, v214
	v_lshl_add_u32 v214, s24, 4, v214
	v_lshrrev_b32_e32 v216, 2, v166
	v_and_b32_e32 v216, 12, v216
	v_add_u32_e32 v216, v216, v211
	v_lshl_add_u32 v216, s24, 8, v216
	v_lshlrev_b32_e32 v216, 2, v216
	s_add_i32 s74, s74, 1
	s_lshl_b64 s[26:27], s[0:1], 20
	s_add_u32 s31, s40, s26
	s_addc_u32 s44, s41, s27
	s_lshl_b32 s0, s24, 8
	s_ashr_i32 s1, s0, 31
	s_lshl_b64 s[24:25], s[0:1], 2
	s_add_u32 s0, s31, s24
	s_mov_b32 s31, 0x3fff80
	s_addc_u32 s1, s44, s25
	s_add_u32 s26, s38, s26
	s_addc_u32 s27, s39, s27
	s_add_u32 s24, s26, s24
	s_addc_u32 s25, s27, s25
	v_readlane_b32 s26, v241, 41
	v_readlane_b32 s27, v241, 42
	v_mov_b32_e32 v217, 0
	s_nop 1
	v_lshl_add_u64 v[216:217], v[216:217], 0, s[26:27]
	global_load_dwordx4 v[218:221], v[216:217], off
	global_load_dwordx4 v[222:225], v[216:217], off offset:64
	global_load_dwordx4 v[226:229], v[216:217], off offset:128
	global_load_dwordx4 v[230:233], v[216:217], off offset:192
	v_mov_b32_e32 v234, v213
	v_mov_b32_e32 v235, 0
	v_lshl_add_u64 v[234:235], v[234:235], 0, s[14:15]
	s_add_u32 s26, s92, 0x35724900
	s_addc_u32 s27, s93, 0
	v_mov_b32_e32 v236, v214
	v_mov_b32_e32 v237, 0
	v_lshl_add_u64 v[236:237], v[236:237], 0, s[26:27]
	v_lshrrev_b32_e32 v250, 1, v166
	v_and_b32_e32 v250, 0x80, v250
	v_and_b32_e32 v251, 15, v166
	v_or_b32_e32 v250, v250, v251
	v_lshrrev_b32_e32 v251, 2, v166
	v_and_b32_e32 v251, 12, v251
	v_and_b32_e32 v252, 0xc0, v166
	v_or_b32_e32 v251, v251, v252
	v_lshl_or_b32 v250, v250, 10, v251
	v_mov_b32_e32 v251, 0
	v_lshl_add_u64 v[246:247], v[250:251], 2, s[0:1]
	v_lshl_add_u64 v[248:249], v[250:251], 2, s[24:25]
	global_load_dwordx4 v[130:133], v[246:247], off
	global_load_dwordx4 v[134:137], v[246:247], off offset:64
	global_load_dwordx4 v[138:141], v[246:247], off offset:128
	global_load_dwordx4 v[142:145], v[246:247], off offset:192
	v_add_co_u32_e32 v246, vcc, 0x10000, v246
	s_nop 1
	v_addc_co_u32_e32 v247, vcc, 0, v247, vcc
	global_load_dwordx4 v[146:149], v[246:247], off
	global_load_dwordx4 v[150:153], v[246:247], off offset:64
	global_load_dwordx4 v[202:205], v[246:247], off offset:128
	global_load_dwordx4 v[206:209], v[246:247], off offset:192
	v_add_co_u32_e32 v246, vcc, 0x10000, v246
	s_nop 1
	v_addc_co_u32_e32 v247, vcc, 0, v247, vcc
	s_waitcnt vmcnt(4)
	v_pk_add_f32 v[126:127], v[126:127], v[130:131]
	v_pk_add_f32 v[128:129], v[128:129], v[132:133]
	v_pk_add_f32 v[122:123], v[122:123], v[134:135]
	v_pk_add_f32 v[124:125], v[124:125], v[136:137]
	v_pk_add_f32 v[118:119], v[118:119], v[138:139]
	v_pk_add_f32 v[120:121], v[120:121], v[140:141]
	v_pk_add_f32 v[114:115], v[114:115], v[142:143]
	v_pk_add_f32 v[116:117], v[116:117], v[144:145]
	global_store_dwordx4 v[248:249], v[126:129], off
	global_store_dwordx4 v[248:249], v[122:125], off offset:64
	global_store_dwordx4 v[248:249], v[118:121], off offset:128
	global_store_dwordx4 v[248:249], v[114:117], off offset:192
	v_add_co_u32_e32 v248, vcc, 0x10000, v248
	s_nop 1
	v_addc_co_u32_e32 v249, vcc, 0, v249, vcc
	v_pk_mul_f32 v[238:239], v[126:127], v[218:219]
	v_pk_mul_f32 v[250:251], v[128:129], v[220:221]
	v_cvt_pk_bf16_f32 v252, v238, v239
	v_cvt_pk_bf16_f32 v253, v250, v251
	v_pk_mul_f32 v[238:239], v[122:123], v[222:223]
	v_pk_mul_f32 v[250:251], v[124:125], v[224:225]
	v_cvt_pk_bf16_f32 v254, v238, v239
	v_cvt_pk_bf16_f32 v255, v250, v251
	s_nop 1
	v_permlane16_swap_b32_e32 v252, v254
	v_permlane16_swap_b32_e32 v253, v255
	global_store_dwordx4 v[234:235], v[252:255], off
	v_pk_mul_f32 v[238:239], v[118:119], v[226:227]
	v_pk_mul_f32 v[250:251], v[120:121], v[228:229]
	v_cvt_pk_bf16_f32 v252, v238, v239
	v_cvt_pk_bf16_f32 v253, v250, v251
	v_pk_mul_f32 v[238:239], v[114:115], v[230:231]
	v_pk_mul_f32 v[250:251], v[116:117], v[232:233]
	v_cvt_pk_bf16_f32 v254, v238, v239
	v_cvt_pk_bf16_f32 v255, v250, v251
	s_nop 1
	v_permlane16_swap_b32_e32 v252, v254
	v_permlane16_swap_b32_e32 v253, v255
	global_store_dwordx4 v[234:235], v[252:255], off offset:64
	v_pk_mul_f32 v[210:211], v[126:127], v[126:127]
	v_pk_fma_f32 v[210:211], v[128:129], v[128:129], v[210:211]
	v_pk_fma_f32 v[210:211], v[122:123], v[122:123], v[210:211]
	v_pk_fma_f32 v[210:211], v[124:125], v[124:125], v[210:211]
	v_pk_fma_f32 v[210:211], v[118:119], v[118:119], v[210:211]
	v_pk_fma_f32 v[210:211], v[120:121], v[120:121], v[210:211]
	v_pk_fma_f32 v[210:211], v[114:115], v[114:115], v[210:211]
	v_pk_fma_f32 v[210:211], v[116:117], v[116:117], v[210:211]
	v_add_f32_e32 v212, v210, v211
	v_mov_b32_e32 v213, v212
	v_mov_b32_e32 v214, v212
	s_nop 1
	v_permlane32_swap_b32_e32 v213, v214
	v_add_f32_e32 v212, v213, v214
	v_mov_b32_e32 v213, v212
	v_mov_b32_e32 v214, v212
	s_nop 1
	v_permlane16_swap_b32_e32 v213, v214
	v_add_f32_e32 v212, v213, v214
	s_mov_b64 exec, 0xffff
	global_store_dword v[236:237], v212, off
	s_mov_b64 exec, -1
	v_add_co_u32_e32 v234, vcc, 0x8000, v234
	s_nop 1
	v_addc_co_u32_e32 v235, vcc, 0, v235, vcc
	v_add_co_u32_e32 v236, vcc, 0x400, v236
	s_nop 1
	v_addc_co_u32_e32 v237, vcc, 0, v237, vcc
	global_load_dwordx4 v[130:133], v[246:247], off
	global_load_dwordx4 v[134:137], v[246:247], off offset:64
	global_load_dwordx4 v[138:141], v[246:247], off offset:128
	global_load_dwordx4 v[142:145], v[246:247], off offset:192
	v_add_co_u32_e32 v246, vcc, 0x10000, v246
	s_nop 1
	v_addc_co_u32_e32 v247, vcc, 0, v247, vcc
	global_load_dwordx4 v[126:129], v[246:247], off
	global_load_dwordx4 v[122:125], v[246:247], off offset:64
	global_load_dwordx4 v[118:121], v[246:247], off offset:128
	global_load_dwordx4 v[114:117], v[246:247], off offset:192
	v_add_co_u32_e32 v246, vcc, 0x10000, v246
	s_nop 1
	v_addc_co_u32_e32 v247, vcc, 0, v247, vcc
	s_waitcnt vmcnt(15)
	v_pk_add_f32 v[110:111], v[110:111], v[146:147]
	v_pk_add_f32 v[112:113], v[112:113], v[148:149]
	v_pk_add_f32 v[106:107], v[106:107], v[150:151]
	v_pk_add_f32 v[108:109], v[108:109], v[152:153]
	v_pk_add_f32 v[102:103], v[102:103], v[202:203]
	v_pk_add_f32 v[104:105], v[104:105], v[204:205]
	v_pk_add_f32 v[98:99], v[98:99], v[206:207]
	v_pk_add_f32 v[100:101], v[100:101], v[208:209]
	global_store_dwordx4 v[248:249], v[110:113], off
	global_store_dwordx4 v[248:249], v[106:109], off offset:64
	global_store_dwordx4 v[248:249], v[102:105], off offset:128
	global_store_dwordx4 v[248:249], v[98:101], off offset:192
	v_add_co_u32_e32 v248, vcc, 0x10000, v248
	s_nop 1
	v_addc_co_u32_e32 v249, vcc, 0, v249, vcc
	v_pk_mul_f32 v[238:239], v[110:111], v[218:219]
	v_pk_mul_f32 v[250:251], v[112:113], v[220:221]
	v_cvt_pk_bf16_f32 v252, v238, v239
	v_cvt_pk_bf16_f32 v253, v250, v251
	v_pk_mul_f32 v[238:239], v[106:107], v[222:223]
	v_pk_mul_f32 v[250:251], v[108:109], v[224:225]
	v_cvt_pk_bf16_f32 v254, v238, v239
	v_cvt_pk_bf16_f32 v255, v250, v251
	s_nop 1
	v_permlane16_swap_b32_e32 v252, v254
	v_permlane16_swap_b32_e32 v253, v255
	global_store_dwordx4 v[234:235], v[252:255], off
	v_pk_mul_f32 v[238:239], v[102:103], v[226:227]
	v_pk_mul_f32 v[250:251], v[104:105], v[228:229]
	v_cvt_pk_bf16_f32 v252, v238, v239
	v_cvt_pk_bf16_f32 v253, v250, v251
	v_pk_mul_f32 v[238:239], v[98:99], v[230:231]
	v_pk_mul_f32 v[250:251], v[100:101], v[232:233]
	v_cvt_pk_bf16_f32 v254, v238, v239
	v_cvt_pk_bf16_f32 v255, v250, v251
	s_nop 1
	v_permlane16_swap_b32_e32 v252, v254
	v_permlane16_swap_b32_e32 v253, v255
	global_store_dwordx4 v[234:235], v[252:255], off offset:64
	v_pk_mul_f32 v[210:211], v[110:111], v[110:111]
	v_pk_fma_f32 v[210:211], v[112:113], v[112:113], v[210:211]
	v_pk_fma_f32 v[210:211], v[106:107], v[106:107], v[210:211]
	v_pk_fma_f32 v[210:211], v[108:109], v[108:109], v[210:211]
	v_pk_fma_f32 v[210:211], v[102:103], v[102:103], v[210:211]
	v_pk_fma_f32 v[210:211], v[104:105], v[104:105], v[210:211]
	v_pk_fma_f32 v[210:211], v[98:99], v[98:99], v[210:211]
	v_pk_fma_f32 v[210:211], v[100:101], v[100:101], v[210:211]
	v_add_f32_e32 v212, v210, v211
	v_mov_b32_e32 v213, v212
	v_mov_b32_e32 v214, v212
	s_nop 1
	v_permlane32_swap_b32_e32 v213, v214
	v_add_f32_e32 v212, v213, v214
	v_mov_b32_e32 v213, v212
	v_mov_b32_e32 v214, v212
	s_nop 1
	v_permlane16_swap_b32_e32 v213, v214
	v_add_f32_e32 v212, v213, v214
	s_mov_b64 exec, 0xffff
	global_store_dword v[236:237], v212, off
	s_mov_b64 exec, -1
	v_add_co_u32_e32 v234, vcc, 0x8000, v234
	s_nop 1
	v_addc_co_u32_e32 v235, vcc, 0, v235, vcc
	v_add_co_u32_e32 v236, vcc, 0x400, v236
	s_nop 1
	v_addc_co_u32_e32 v237, vcc, 0, v237, vcc
	global_load_dwordx4 v[146:149], v[246:247], off
	global_load_dwordx4 v[150:153], v[246:247], off offset:64
	global_load_dwordx4 v[202:205], v[246:247], off offset:128
	global_load_dwordx4 v[206:209], v[246:247], off offset:192
	v_add_co_u32_e32 v246, vcc, 0x10000, v246
	s_nop 1
	v_addc_co_u32_e32 v247, vcc, 0, v247, vcc
	global_load_dwordx4 v[110:113], v[246:247], off
	global_load_dwordx4 v[106:109], v[246:247], off offset:64
	global_load_dwordx4 v[102:105], v[246:247], off offset:128
	global_load_dwordx4 v[98:101], v[246:247], off offset:192
	v_add_co_u32_e32 v246, vcc, 0x10000, v246
	s_nop 1
	v_addc_co_u32_e32 v247, vcc, 0, v247, vcc
	s_waitcnt vmcnt(19)
	v_pk_add_f32 v[94:95], v[94:95], v[130:131]
	v_pk_add_f32 v[96:97], v[96:97], v[132:133]
	v_pk_add_f32 v[90:91], v[90:91], v[134:135]
	v_pk_add_f32 v[92:93], v[92:93], v[136:137]
	v_pk_add_f32 v[86:87], v[86:87], v[138:139]
	v_pk_add_f32 v[88:89], v[88:89], v[140:141]
	v_pk_add_f32 v[82:83], v[82:83], v[142:143]
	v_pk_add_f32 v[84:85], v[84:85], v[144:145]
	global_store_dwordx4 v[248:249], v[94:97], off
	global_store_dwordx4 v[248:249], v[90:93], off offset:64
	global_store_dwordx4 v[248:249], v[86:89], off offset:128
	global_store_dwordx4 v[248:249], v[82:85], off offset:192
	v_add_co_u32_e32 v248, vcc, 0x10000, v248
	s_nop 1
	v_addc_co_u32_e32 v249, vcc, 0, v249, vcc
	v_pk_mul_f32 v[238:239], v[94:95], v[218:219]
	v_pk_mul_f32 v[250:251], v[96:97], v[220:221]
	v_cvt_pk_bf16_f32 v252, v238, v239
	v_cvt_pk_bf16_f32 v253, v250, v251
	v_pk_mul_f32 v[238:239], v[90:91], v[222:223]
	v_pk_mul_f32 v[250:251], v[92:93], v[224:225]
	v_cvt_pk_bf16_f32 v254, v238, v239
	v_cvt_pk_bf16_f32 v255, v250, v251
	s_nop 1
	v_permlane16_swap_b32_e32 v252, v254
	v_permlane16_swap_b32_e32 v253, v255
	global_store_dwordx4 v[234:235], v[252:255], off
	v_pk_mul_f32 v[238:239], v[86:87], v[226:227]
	v_pk_mul_f32 v[250:251], v[88:89], v[228:229]
	v_cvt_pk_bf16_f32 v252, v238, v239
	v_cvt_pk_bf16_f32 v253, v250, v251
	v_pk_mul_f32 v[238:239], v[82:83], v[230:231]
	v_pk_mul_f32 v[250:251], v[84:85], v[232:233]
	v_cvt_pk_bf16_f32 v254, v238, v239
	v_cvt_pk_bf16_f32 v255, v250, v251
	s_nop 1
	v_permlane16_swap_b32_e32 v252, v254
	v_permlane16_swap_b32_e32 v253, v255
	global_store_dwordx4 v[234:235], v[252:255], off offset:64
	v_pk_mul_f32 v[210:211], v[94:95], v[94:95]
	v_pk_fma_f32 v[210:211], v[96:97], v[96:97], v[210:211]
	v_pk_fma_f32 v[210:211], v[90:91], v[90:91], v[210:211]
	v_pk_fma_f32 v[210:211], v[92:93], v[92:93], v[210:211]
	v_pk_fma_f32 v[210:211], v[86:87], v[86:87], v[210:211]
	v_pk_fma_f32 v[210:211], v[88:89], v[88:89], v[210:211]
	v_pk_fma_f32 v[210:211], v[82:83], v[82:83], v[210:211]
	v_pk_fma_f32 v[210:211], v[84:85], v[84:85], v[210:211]
	v_add_f32_e32 v212, v210, v211
	v_mov_b32_e32 v213, v212
	v_mov_b32_e32 v214, v212
	s_nop 1
	v_permlane32_swap_b32_e32 v213, v214
	v_add_f32_e32 v212, v213, v214
	v_mov_b32_e32 v213, v212
	v_mov_b32_e32 v214, v212
	s_nop 1
	v_permlane16_swap_b32_e32 v213, v214
	v_add_f32_e32 v212, v213, v214
	s_mov_b64 exec, 0xffff
	global_store_dword v[236:237], v212, off
	s_mov_b64 exec, -1
	v_add_co_u32_e32 v234, vcc, 0x8000, v234
	s_nop 1
	v_addc_co_u32_e32 v235, vcc, 0, v235, vcc
	v_add_co_u32_e32 v236, vcc, 0x400, v236
	s_nop 1
	v_addc_co_u32_e32 v237, vcc, 0, v237, vcc
	global_load_dwordx4 v[130:133], v[246:247], off
	global_load_dwordx4 v[134:137], v[246:247], off offset:64
	global_load_dwordx4 v[138:141], v[246:247], off offset:128
	global_load_dwordx4 v[142:145], v[246:247], off offset:192
	v_add_co_u32_e32 v246, vcc, 0x10000, v246
	s_nop 1
	v_addc_co_u32_e32 v247, vcc, 0, v247, vcc
	global_load_dwordx4 v[94:97], v[246:247], off
	global_load_dwordx4 v[90:93], v[246:247], off offset:64
	global_load_dwordx4 v[86:89], v[246:247], off offset:128
	global_load_dwordx4 v[82:85], v[246:247], off offset:192
	s_waitcnt vmcnt(30)
	v_pk_add_f32 v[78:79], v[78:79], v[126:127]
	v_pk_add_f32 v[80:81], v[80:81], v[128:129]
	v_pk_add_f32 v[74:75], v[74:75], v[122:123]
	v_pk_add_f32 v[76:77], v[76:77], v[124:125]
	v_pk_add_f32 v[70:71], v[70:71], v[118:119]
	v_pk_add_f32 v[72:73], v[72:73], v[120:121]
	v_pk_add_f32 v[66:67], v[66:67], v[114:115]
	v_pk_add_f32 v[68:69], v[68:69], v[116:117]
	global_store_dwordx4 v[248:249], v[78:81], off
	global_store_dwordx4 v[248:249], v[74:77], off offset:64
	global_store_dwordx4 v[248:249], v[70:73], off offset:128
	global_store_dwordx4 v[248:249], v[66:69], off offset:192
	v_add_co_u32_e32 v248, vcc, 0x10000, v248
	s_nop 1
	v_addc_co_u32_e32 v249, vcc, 0, v249, vcc
	v_pk_mul_f32 v[238:239], v[78:79], v[218:219]
	v_pk_mul_f32 v[250:251], v[80:81], v[220:221]
	v_cvt_pk_bf16_f32 v252, v238, v239
	v_cvt_pk_bf16_f32 v253, v250, v251
	v_pk_mul_f32 v[238:239], v[74:75], v[222:223]
	v_pk_mul_f32 v[250:251], v[76:77], v[224:225]
	v_cvt_pk_bf16_f32 v254, v238, v239
	v_cvt_pk_bf16_f32 v255, v250, v251
	s_nop 1
	v_permlane16_swap_b32_e32 v252, v254
	v_permlane16_swap_b32_e32 v253, v255
	global_store_dwordx4 v[234:235], v[252:255], off
	v_pk_mul_f32 v[238:239], v[70:71], v[226:227]
	v_pk_mul_f32 v[250:251], v[72:73], v[228:229]
	v_cvt_pk_bf16_f32 v252, v238, v239
	v_cvt_pk_bf16_f32 v253, v250, v251
	v_pk_mul_f32 v[238:239], v[66:67], v[230:231]
	v_pk_mul_f32 v[250:251], v[68:69], v[232:233]
	v_cvt_pk_bf16_f32 v254, v238, v239
	v_cvt_pk_bf16_f32 v255, v250, v251
	s_nop 1
	v_permlane16_swap_b32_e32 v252, v254
	v_permlane16_swap_b32_e32 v253, v255
	global_store_dwordx4 v[234:235], v[252:255], off offset:64
	v_pk_mul_f32 v[210:211], v[78:79], v[78:79]
	v_pk_fma_f32 v[210:211], v[80:81], v[80:81], v[210:211]
	v_pk_fma_f32 v[210:211], v[74:75], v[74:75], v[210:211]
	v_pk_fma_f32 v[210:211], v[76:77], v[76:77], v[210:211]
	v_pk_fma_f32 v[210:211], v[70:71], v[70:71], v[210:211]
	v_pk_fma_f32 v[210:211], v[72:73], v[72:73], v[210:211]
	v_pk_fma_f32 v[210:211], v[66:67], v[66:67], v[210:211]
	v_pk_fma_f32 v[210:211], v[68:69], v[68:69], v[210:211]
	v_add_f32_e32 v212, v210, v211
	v_mov_b32_e32 v213, v212
	v_mov_b32_e32 v214, v212
	s_nop 1
	v_permlane32_swap_b32_e32 v213, v214
	v_add_f32_e32 v212, v213, v214
	v_mov_b32_e32 v213, v212
	v_mov_b32_e32 v214, v212
	s_nop 1
	v_permlane16_swap_b32_e32 v213, v214
	v_add_f32_e32 v212, v213, v214
	s_mov_b64 exec, 0xffff
	global_store_dword v[236:237], v212, off
	s_mov_b64 exec, -1
	v_add_co_u32_e32 v234, vcc, 0x8000, v234
	s_nop 1
	v_addc_co_u32_e32 v235, vcc, 0, v235, vcc
	v_add_co_u32_e32 v236, vcc, 0x400, v236
	s_nop 1
	v_addc_co_u32_e32 v237, vcc, 0, v237, vcc
	s_waitcnt vmcnt(26)
	v_pk_add_f32 v[60:61], v[60:61], v[146:147]
	v_pk_add_f32 v[62:63], v[62:63], v[148:149]
	v_pk_add_f32 v[56:57], v[56:57], v[150:151]
	v_pk_add_f32 v[58:59], v[58:59], v[152:153]
	v_pk_add_f32 v[52:53], v[52:53], v[202:203]
	v_pk_add_f32 v[54:55], v[54:55], v[204:205]
	v_pk_add_f32 v[48:49], v[48:49], v[206:207]
	v_pk_add_f32 v[50:51], v[50:51], v[208:209]
	global_store_dwordx4 v[248:249], v[60:63], off
	global_store_dwordx4 v[248:249], v[56:59], off offset:64
	global_store_dwordx4 v[248:249], v[52:55], off offset:128
	global_store_dwordx4 v[248:249], v[48:51], off offset:192
	v_add_co_u32_e32 v248, vcc, 0x10000, v248
	s_nop 1
	v_addc_co_u32_e32 v249, vcc, 0, v249, vcc
	v_pk_mul_f32 v[238:239], v[60:61], v[218:219]
	v_pk_mul_f32 v[250:251], v[62:63], v[220:221]
	v_cvt_pk_bf16_f32 v252, v238, v239
	v_cvt_pk_bf16_f32 v253, v250, v251
	v_pk_mul_f32 v[238:239], v[56:57], v[222:223]
	v_pk_mul_f32 v[250:251], v[58:59], v[224:225]
	v_cvt_pk_bf16_f32 v254, v238, v239
	v_cvt_pk_bf16_f32 v255, v250, v251
	s_nop 1
	v_permlane16_swap_b32_e32 v252, v254
	v_permlane16_swap_b32_e32 v253, v255
	global_store_dwordx4 v[234:235], v[252:255], off
	v_pk_mul_f32 v[238:239], v[52:53], v[226:227]
	v_pk_mul_f32 v[250:251], v[54:55], v[228:229]
	v_cvt_pk_bf16_f32 v252, v238, v239
	v_cvt_pk_bf16_f32 v253, v250, v251
	v_pk_mul_f32 v[238:239], v[48:49], v[230:231]
	v_pk_mul_f32 v[250:251], v[50:51], v[232:233]
	v_cvt_pk_bf16_f32 v254, v238, v239
	v_cvt_pk_bf16_f32 v255, v250, v251
	s_nop 1
	v_permlane16_swap_b32_e32 v252, v254
	v_permlane16_swap_b32_e32 v253, v255
	global_store_dwordx4 v[234:235], v[252:255], off offset:64
	v_pk_mul_f32 v[210:211], v[60:61], v[60:61]
	v_pk_fma_f32 v[210:211], v[62:63], v[62:63], v[210:211]
	v_pk_fma_f32 v[210:211], v[56:57], v[56:57], v[210:211]
	v_pk_fma_f32 v[210:211], v[58:59], v[58:59], v[210:211]
	v_pk_fma_f32 v[210:211], v[52:53], v[52:53], v[210:211]
	v_pk_fma_f32 v[210:211], v[54:55], v[54:55], v[210:211]
	v_pk_fma_f32 v[210:211], v[48:49], v[48:49], v[210:211]
	v_pk_fma_f32 v[210:211], v[50:51], v[50:51], v[210:211]
	v_add_f32_e32 v212, v210, v211
	v_mov_b32_e32 v213, v212
	v_mov_b32_e32 v214, v212
	s_nop 1
	v_permlane32_swap_b32_e32 v213, v214
	v_add_f32_e32 v212, v213, v214
	v_mov_b32_e32 v213, v212
	v_mov_b32_e32 v214, v212
	s_nop 1
	v_permlane16_swap_b32_e32 v213, v214
	v_add_f32_e32 v212, v213, v214
	s_mov_b64 exec, 0xffff
	global_store_dword v[236:237], v212, off
	s_mov_b64 exec, -1
	v_add_co_u32_e32 v234, vcc, 0x8000, v234
	s_nop 1
	v_addc_co_u32_e32 v235, vcc, 0, v235, vcc
	v_add_co_u32_e32 v236, vcc, 0x400, v236
	s_nop 1
	v_addc_co_u32_e32 v237, vcc, 0, v237, vcc
	s_waitcnt vmcnt(29)
	v_pk_add_f32 v[44:45], v[44:45], v[110:111]
	v_pk_add_f32 v[46:47], v[46:47], v[112:113]
	v_pk_add_f32 v[40:41], v[40:41], v[106:107]
	v_pk_add_f32 v[42:43], v[42:43], v[108:109]
	v_pk_add_f32 v[36:37], v[36:37], v[102:103]
	v_pk_add_f32 v[38:39], v[38:39], v[104:105]
	v_pk_add_f32 v[32:33], v[32:33], v[98:99]
	v_pk_add_f32 v[34:35], v[34:35], v[100:101]
	global_store_dwordx4 v[248:249], v[44:47], off
	global_store_dwordx4 v[248:249], v[40:43], off offset:64
	global_store_dwordx4 v[248:249], v[36:39], off offset:128
	global_store_dwordx4 v[248:249], v[32:35], off offset:192
	v_add_co_u32_e32 v248, vcc, 0x10000, v248
	s_nop 1
	v_addc_co_u32_e32 v249, vcc, 0, v249, vcc
	v_pk_mul_f32 v[238:239], v[44:45], v[218:219]
	v_pk_mul_f32 v[250:251], v[46:47], v[220:221]
	v_cvt_pk_bf16_f32 v252, v238, v239
	v_cvt_pk_bf16_f32 v253, v250, v251
	v_pk_mul_f32 v[238:239], v[40:41], v[222:223]
	v_pk_mul_f32 v[250:251], v[42:43], v[224:225]
	v_cvt_pk_bf16_f32 v254, v238, v239
	v_cvt_pk_bf16_f32 v255, v250, v251
	s_nop 1
	v_permlane16_swap_b32_e32 v252, v254
	v_permlane16_swap_b32_e32 v253, v255
	global_store_dwordx4 v[234:235], v[252:255], off
	v_pk_mul_f32 v[238:239], v[36:37], v[226:227]
	v_pk_mul_f32 v[250:251], v[38:39], v[228:229]
	v_cvt_pk_bf16_f32 v252, v238, v239
	v_cvt_pk_bf16_f32 v253, v250, v251
	v_pk_mul_f32 v[238:239], v[32:33], v[230:231]
	v_pk_mul_f32 v[250:251], v[34:35], v[232:233]
	v_cvt_pk_bf16_f32 v254, v238, v239
	v_cvt_pk_bf16_f32 v255, v250, v251
	s_nop 1
	v_permlane16_swap_b32_e32 v252, v254
	v_permlane16_swap_b32_e32 v253, v255
	global_store_dwordx4 v[234:235], v[252:255], off offset:64
	v_pk_mul_f32 v[210:211], v[44:45], v[44:45]
	v_pk_fma_f32 v[210:211], v[46:47], v[46:47], v[210:211]
	v_pk_fma_f32 v[210:211], v[40:41], v[40:41], v[210:211]
	v_pk_fma_f32 v[210:211], v[42:43], v[42:43], v[210:211]
	v_pk_fma_f32 v[210:211], v[36:37], v[36:37], v[210:211]
	v_pk_fma_f32 v[210:211], v[38:39], v[38:39], v[210:211]
	v_pk_fma_f32 v[210:211], v[32:33], v[32:33], v[210:211]
	v_pk_fma_f32 v[210:211], v[34:35], v[34:35], v[210:211]
	v_add_f32_e32 v212, v210, v211
	v_mov_b32_e32 v213, v212
	v_mov_b32_e32 v214, v212
	s_nop 1
	v_permlane32_swap_b32_e32 v213, v214
	v_add_f32_e32 v212, v213, v214
	v_mov_b32_e32 v213, v212
	v_mov_b32_e32 v214, v212
	s_nop 1
	v_permlane16_swap_b32_e32 v213, v214
	v_add_f32_e32 v212, v213, v214
	s_mov_b64 exec, 0xffff
	global_store_dword v[236:237], v212, off
	s_mov_b64 exec, -1
	v_add_co_u32_e32 v234, vcc, 0x8000, v234
	s_nop 1
	v_addc_co_u32_e32 v235, vcc, 0, v235, vcc
	v_add_co_u32_e32 v236, vcc, 0x400, v236
	s_nop 1
	v_addc_co_u32_e32 v237, vcc, 0, v237, vcc
	s_waitcnt vmcnt(25)
	v_pk_add_f32 v[28:29], v[28:29], v[130:131]
	v_pk_add_f32 v[30:31], v[30:31], v[132:133]
	v_pk_add_f32 v[24:25], v[24:25], v[134:135]
	v_pk_add_f32 v[26:27], v[26:27], v[136:137]
	v_pk_add_f32 v[20:21], v[20:21], v[138:139]
	v_pk_add_f32 v[22:23], v[22:23], v[140:141]
	v_pk_add_f32 v[16:17], v[16:17], v[142:143]
	v_pk_add_f32 v[18:19], v[18:19], v[144:145]
	global_store_dwordx4 v[248:249], v[28:31], off
	global_store_dwordx4 v[248:249], v[24:27], off offset:64
	global_store_dwordx4 v[248:249], v[20:23], off offset:128
	global_store_dwordx4 v[248:249], v[16:19], off offset:192
	v_add_co_u32_e32 v248, vcc, 0x10000, v248
	s_nop 1
	v_addc_co_u32_e32 v249, vcc, 0, v249, vcc
	v_pk_mul_f32 v[238:239], v[28:29], v[218:219]
	v_pk_mul_f32 v[250:251], v[30:31], v[220:221]
	v_cvt_pk_bf16_f32 v252, v238, v239
	v_cvt_pk_bf16_f32 v253, v250, v251
	v_pk_mul_f32 v[238:239], v[24:25], v[222:223]
	v_pk_mul_f32 v[250:251], v[26:27], v[224:225]
	v_cvt_pk_bf16_f32 v254, v238, v239
	v_cvt_pk_bf16_f32 v255, v250, v251
	s_nop 1
	v_permlane16_swap_b32_e32 v252, v254
	v_permlane16_swap_b32_e32 v253, v255
	global_store_dwordx4 v[234:235], v[252:255], off
	v_pk_mul_f32 v[238:239], v[20:21], v[226:227]
	v_pk_mul_f32 v[250:251], v[22:23], v[228:229]
	v_cvt_pk_bf16_f32 v252, v238, v239
	v_cvt_pk_bf16_f32 v253, v250, v251
	v_pk_mul_f32 v[238:239], v[16:17], v[230:231]
	v_pk_mul_f32 v[250:251], v[18:19], v[232:233]
	v_cvt_pk_bf16_f32 v254, v238, v239
	v_cvt_pk_bf16_f32 v255, v250, v251
	s_nop 1
	v_permlane16_swap_b32_e32 v252, v254
	v_permlane16_swap_b32_e32 v253, v255
	global_store_dwordx4 v[234:235], v[252:255], off offset:64
	v_pk_mul_f32 v[210:211], v[28:29], v[28:29]
	v_pk_fma_f32 v[210:211], v[30:31], v[30:31], v[210:211]
	v_pk_fma_f32 v[210:211], v[24:25], v[24:25], v[210:211]
	v_pk_fma_f32 v[210:211], v[26:27], v[26:27], v[210:211]
	v_pk_fma_f32 v[210:211], v[20:21], v[20:21], v[210:211]
	v_pk_fma_f32 v[210:211], v[22:23], v[22:23], v[210:211]
	v_pk_fma_f32 v[210:211], v[16:17], v[16:17], v[210:211]
	v_pk_fma_f32 v[210:211], v[18:19], v[18:19], v[210:211]
	v_add_f32_e32 v212, v210, v211
	v_mov_b32_e32 v213, v212
	v_mov_b32_e32 v214, v212
	s_nop 1
	v_permlane32_swap_b32_e32 v213, v214
	v_add_f32_e32 v212, v213, v214
	v_mov_b32_e32 v213, v212
	v_mov_b32_e32 v214, v212
	s_nop 1
	v_permlane16_swap_b32_e32 v213, v214
	v_add_f32_e32 v212, v213, v214
	s_mov_b64 exec, 0xffff
	global_store_dword v[236:237], v212, off
	s_mov_b64 exec, -1
	v_add_co_u32_e32 v234, vcc, 0x8000, v234
	s_nop 1
	v_addc_co_u32_e32 v235, vcc, 0, v235, vcc
	v_add_co_u32_e32 v236, vcc, 0x400, v236
	s_nop 1
	v_addc_co_u32_e32 v237, vcc, 0, v237, vcc
	s_waitcnt vmcnt(28)
	v_pk_add_f32 v[12:13], v[12:13], v[94:95]
	v_pk_add_f32 v[14:15], v[14:15], v[96:97]
	v_pk_add_f32 v[8:9], v[8:9], v[90:91]
	v_pk_add_f32 v[10:11], v[10:11], v[92:93]
	v_pk_add_f32 v[4:5], v[4:5], v[86:87]
	v_pk_add_f32 v[6:7], v[6:7], v[88:89]
	v_pk_add_f32 v[0:1], v[0:1], v[82:83]
	v_pk_add_f32 v[2:3], v[2:3], v[84:85]
	global_store_dwordx4 v[248:249], v[12:15], off
	global_store_dwordx4 v[248:249], v[8:11], off offset:64
	global_store_dwordx4 v[248:249], v[4:7], off offset:128
	global_store_dwordx4 v[248:249], v[0:3], off offset:192
	v_pk_mul_f32 v[238:239], v[12:13], v[218:219]
	v_pk_mul_f32 v[250:251], v[14:15], v[220:221]
	v_cvt_pk_bf16_f32 v252, v238, v239
	v_cvt_pk_bf16_f32 v253, v250, v251
	v_pk_mul_f32 v[238:239], v[8:9], v[222:223]
	v_pk_mul_f32 v[250:251], v[10:11], v[224:225]
	v_cvt_pk_bf16_f32 v254, v238, v239
	v_cvt_pk_bf16_f32 v255, v250, v251
	s_nop 1
	v_permlane16_swap_b32_e32 v252, v254
	v_permlane16_swap_b32_e32 v253, v255
	global_store_dwordx4 v[234:235], v[252:255], off
	v_pk_mul_f32 v[238:239], v[4:5], v[226:227]
	v_pk_mul_f32 v[250:251], v[6:7], v[228:229]
	v_cvt_pk_bf16_f32 v252, v238, v239
	v_cvt_pk_bf16_f32 v253, v250, v251
	v_pk_mul_f32 v[238:239], v[0:1], v[230:231]
	v_pk_mul_f32 v[250:251], v[2:3], v[232:233]
	v_cvt_pk_bf16_f32 v254, v238, v239
	v_cvt_pk_bf16_f32 v255, v250, v251
	s_nop 1
	v_permlane16_swap_b32_e32 v252, v254
	v_permlane16_swap_b32_e32 v253, v255
	global_store_dwordx4 v[234:235], v[252:255], off offset:64
	v_pk_mul_f32 v[210:211], v[12:13], v[12:13]
	v_pk_fma_f32 v[210:211], v[14:15], v[14:15], v[210:211]
	v_pk_fma_f32 v[210:211], v[8:9], v[8:9], v[210:211]
	v_pk_fma_f32 v[210:211], v[10:11], v[10:11], v[210:211]
	v_pk_fma_f32 v[210:211], v[4:5], v[4:5], v[210:211]
	v_pk_fma_f32 v[210:211], v[6:7], v[6:7], v[210:211]
	v_pk_fma_f32 v[210:211], v[0:1], v[0:1], v[210:211]
	v_pk_fma_f32 v[210:211], v[2:3], v[2:3], v[210:211]
	v_add_f32_e32 v212, v210, v211
	v_mov_b32_e32 v213, v212
	v_mov_b32_e32 v214, v212
	s_nop 1
	v_permlane32_swap_b32_e32 v213, v214
	v_add_f32_e32 v212, v213, v214
	v_mov_b32_e32 v213, v212
	v_mov_b32_e32 v214, v212
	s_nop 1
	v_permlane16_swap_b32_e32 v213, v214
	v_add_f32_e32 v212, v213, v214
	s_mov_b64 exec, 0xffff
	global_store_dword v[236:237], v212, off
	s_mov_b64 exec, -1
	s_andn2_b64 vcc, exec, s[28:29]
	s_cbranch_vccz .LBB0_1297

.Lg3_X:
	s_waitcnt lgkmcnt(0)
	v_mfma_f32_16x16x32_bf16 v[28:31], v[130:133], v[202:205], v[28:31]
	v_mfma_f32_16x16x32_bf16 v[24:27], v[134:137], v[202:205], v[24:27]
	v_mfma_f32_16x16x32_bf16 v[20:23], v[138:141], v[202:205], v[20:23]
	v_mfma_f32_16x16x32_bf16 v[16:19], v[142:145], v[202:205], v[16:19]
	v_mfma_f32_16x16x32_bf16 v[12:15], v[130:133], v[206:209], v[12:15]
	v_mfma_f32_16x16x32_bf16 v[8:11], v[134:137], v[206:209], v[8:11]
	v_mfma_f32_16x16x32_bf16 v[4:7], v[138:141], v[206:209], v[4:7]
	v_mfma_f32_16x16x32_bf16 v[0:3], v[142:145], v[206:209], v[0:3]
	s_nop 7
	s_nop 1
	s_branch .LBB0_1286
.Ltramp502:
	s_branch .LBB0_502
.LBB0_1286:
	s_and_b64 vcc, exec, s[36:37]
	s_mov_b64 s[26:27], -1
	s_cbranch_vccnz .LBB0_1288
	s_mul_i32 s25, s74, s94
	s_add_i32 s25, s25, s2
	s_mov_b64 s[26:27], 0

.LBB0_1351:
	s_or_b64 exec, exec, s[0:1]
	s_branch .LBB0_1407
	v_mov_b32_e32 v0, v166
	s_barrier
	v_readlane_b32 s0, v244, 3
	v_ashrrev_i32_e32 v1, 6, v0
	s_nop 0
	v_add_u32_e32 v24, s0, v1
	s_movk_i32 s0, 0x4000
	v_cmp_gt_i32_e32 vcc, s0, v24
	s_and_saveexec_b64 s[24:25], vcc
	s_cbranch_execz .LBB0_1354
	v_and_b32_e32 v16, 63, v0
	v_readlane_b32 s0, v241, 41
	v_lshlrev_b32_e32 v64, 4, v16
	v_readlane_b32 s1, v241, 42
	s_nop 4
	global_load_dwordx4 v[0:3], v64, s[0:1]
	global_load_dwordx4 v[4:7], v64, s[0:1] offset:1024
	global_load_dwordx4 v[8:11], v64, s[0:1] offset:2048
	global_load_dwordx4 v[12:15], v64, s[0:1] offset:3072
	v_cmp_lt_i32_e32 vcc, v157, v168
	v_lshlrev_b32_e32 v16, 2, v16
	v_or_b32_e32 v18, 0x100, v16
	v_cndmask_b32_e32 v17, v155, v157, vcc
	v_cmp_lt_i32_e32 vcc, v169, v168
	v_lshlrev_b32_e32 v37, 2, v17
	v_or_b32_e32 v20, 0x200, v16
	v_cndmask_b32_e32 v17, v155, v169, vcc
	v_or_b32_e32 v22, 0x300, v16
	v_lshlrev_b32_e32 v38, 2, v17
	v_lshl_add_u64 v[26:27], s[38:39], 0, v[64:65]
	s_mov_b64 s[28:29], 0
	v_lshlrev_b32_e32 v64, 1, v16
	v_lshlrev_b32_e32 v28, 1, v18
	v_lshlrev_b32_e32 v30, 1, v20
	v_lshlrev_b32_e32 v32, 1, v22

.Lg4_X:
	v_lshrrev_b32_e32 v250, 1, v166
	v_and_b32_e32 v250, 0x80, v250
	v_and_b32_e32 v251, 15, v166
	v_or_b32_e32 v250, v250, v251
	v_lshlrev_b32_e32 v250, 6, v250
	v_and_b32_e32 v251, 0x30, v166
	v_or_b32_e32 v250, v250, v251
	s_lshr_b32 s26, s24, 5
	v_add_u32_e32 v250, s26, v250
	v_mov_b32_e32 v251, 0
	s_add_u32 s26, s92, 0x35724900
	s_addc_u32 s27, s93, 0
	v_lshl_add_u64 v[250:251], v[250:251], 0, s[26:27]
	global_load_dwordx4 v[210:213], v[250:251], off
	global_load_dwordx4 v[214:217], v[250:251], off offset:1024
	global_load_dwordx4 v[218:221], v[250:251], off offset:2048
	global_load_dwordx4 v[222:225], v[250:251], off offset:3072
	v_add_co_u32_e32 v250, vcc, 0x1000, v250
	s_nop 1
	v_addc_co_u32_e32 v251, vcc, 0, v251, vcc
	global_load_dwordx4 v[226:229], v[250:251], off
	global_load_dwordx4 v[230:233], v[250:251], off offset:1024
	global_load_dwordx4 v[234:237], v[250:251], off offset:2048
	global_load_dwordx4 v[252:255], v[250:251], off offset:3072
	s_waitcnt lgkmcnt(0)
	v_mfma_f32_16x16x32_bf16 v[24:27], v[130:133], v[202:205], v[24:27]
	v_mfma_f32_16x16x32_bf16 v[20:23], v[134:137], v[202:205], v[20:23]
	v_mfma_f32_16x16x32_bf16 v[16:19], v[138:141], v[202:205], v[16:19]
	v_mfma_f32_16x16x32_bf16 v[12:15], v[142:145], v[202:205], v[12:15]
	v_mfma_f32_16x16x32_bf16 v[8:11], v[130:133], v[206:209], v[8:11]
	v_mfma_f32_16x16x32_bf16 v[4:7], v[134:137], v[206:209], v[4:7]
	v_mfma_f32_16x16x32_bf16 v[0:3], v[138:141], v[206:209], v[0:3]
	v_mfma_f32_16x16x32_bf16 v[28:31], v[142:145], v[206:209], v[28:31]
	s_nop 7
	s_nop 1
	s_branch .LBB0_1428
.LBB0_1428:
	s_lshl_b32 s40, s74, 9
	s_add_u32 s1, s18, s24
	s_addc_u32 s25, s19, s25
	s_lshl_b32 s41, s74, 8
	s_lshl_b32 s84, s74, 9
	s_add_u32 s24, s1, s84
	s_mov_b32 s1, 0x3fff80
	s_addc_u32 s25, s25, 0
	s_bfe_i32 s26, s0, 0x190000
	v_lshrrev_b32_e32 v248, 1, v166
	v_and_b32_e32 v248, 0x80, v248
	v_and_b32_e32 v249, 15, v166
	v_or_b32_e32 v248, v248, v249
	v_and_b32_e32 v249, 16, v166
	v_lshrrev_b32_e32 v250, 2, v166
	v_and_b32_e32 v250, 8, v250
	v_or_b32_e32 v249, v249, v250
	v_and_b32_e32 v250, 0xc0, v166
	v_or_b32_e32 v249, v249, v250
	v_lshl_or_b32 v248, v248, 10, v249
	v_mov_b32_e32 v249, 0
	v_lshl_add_u64 v[246:247], v[248:249], 1, s[24:25]
	v_mov_b32_e32 v130, 0x3a800000
	s_waitcnt vmcnt(7)
	v_add_f32_e32 v132, v210, v211
	v_add_f32_e32 v133, v212, v213
	v_add_f32_e32 v132, v132, v133
	v_mov_b32_e32 v133, v132
	v_mov_b32_e32 v134, v132
	s_nop 1
	v_permlane32_swap_b32_e32 v133, v134
	v_add_f32_e32 v132, v133, v134
	v_mov_b32_e32 v133, v132
	v_mov_b32_e32 v134, v132
	s_nop 1
	v_permlane16_swap_b32_e32 v133, v134
	v_add_f32_e32 v132, v133, v134
	v_fmaak_f32 v133, v132, v130, 0x3727c5ac
	v_rsq_f32_e32 v134, v133
	v_mul_f32_e32 v133, 0.5, v133
	s_nop 0
	v_mul_f32_e32 v132, v133, v134
	v_fma_f32 v132, -v132, v134, 0.5
	v_fma_f32 v136, v134, v132, v134
	v_mul_f32_e32 v136, 0x3d800000, v136
	v_mov_b32_e32 v137, v136
	v_pk_mul_f32 v[126:127], v[126:127], v[136:137]
	v_pk_mul_f32 v[128:129], v[128:129], v[136:137]
	v_pk_mul_f32 v[122:123], v[122:123], v[136:137]
	v_pk_mul_f32 v[124:125], v[124:125], v[136:137]
	v_pk_mul_f32 v[118:119], v[118:119], v[136:137]
	v_pk_mul_f32 v[120:121], v[120:121], v[136:137]
	v_pk_mul_f32 v[114:115], v[114:115], v[136:137]
	v_pk_mul_f32 v[116:117], v[116:117], v[136:137]
	v_cvt_pk_bf16_f32 v126, v126, v127
	v_cvt_pk_bf16_f32 v127, v128, v129
	v_cvt_pk_bf16_f32 v128, v122, v123
	v_cvt_pk_bf16_f32 v129, v124, v125
	v_cvt_pk_bf16_f32 v118, v118, v119
	v_cvt_pk_bf16_f32 v119, v120, v121
	v_cvt_pk_bf16_f32 v120, v114, v115
	v_cvt_pk_bf16_f32 v121, v116, v117
	s_nop 1
	v_permlane16_swap_b32_e32 v126, v128
	v_permlane16_swap_b32_e32 v127, v129
	v_permlane16_swap_b32_e32 v118, v120
	v_permlane16_swap_b32_e32 v119, v121
	global_store_dwordx4 v[246:247], v[126:129], off
	global_store_dwordx4 v[246:247], v[118:121], off offset:64
	v_add_co_u32_e32 v246, vcc, 0x8000, v246
	s_nop 1
	v_addc_co_u32_e32 v247, vcc, 0, v247, vcc
	s_waitcnt vmcnt(8)
	v_add_f32_e32 v132, v214, v215
	v_add_f32_e32 v133, v216, v217
	v_add_f32_e32 v132, v132, v133
	v_mov_b32_e32 v133, v132
	v_mov_b32_e32 v134, v132
	s_nop 1
	v_permlane32_swap_b32_e32 v133, v134
	v_add_f32_e32 v132, v133, v134
	v_mov_b32_e32 v133, v132
	v_mov_b32_e32 v134, v132
	s_nop 1
	v_permlane16_swap_b32_e32 v133, v134
	v_add_f32_e32 v132, v133, v134
	v_fmaak_f32 v133, v132, v130, 0x3727c5ac
	v_rsq_f32_e32 v134, v133
	v_mul_f32_e32 v133, 0.5, v133
	s_nop 0
	v_mul_f32_e32 v132, v133, v134
	v_fma_f32 v132, -v132, v134, 0.5
	v_fma_f32 v136, v134, v132, v134
	v_mul_f32_e32 v136, 0x3d800000, v136
	v_mov_b32_e32 v137, v136
	v_pk_mul_f32 v[110:111], v[110:111], v[136:137]
	v_pk_mul_f32 v[112:113], v[112:113], v[136:137]
	v_pk_mul_f32 v[106:107], v[106:107], v[136:137]
	v_pk_mul_f32 v[108:109], v[108:109], v[136:137]
	v_pk_mul_f32 v[102:103], v[102:103], v[136:137]
	v_pk_mul_f32 v[104:105], v[104:105], v[136:137]
	v_pk_mul_f32 v[98:99], v[98:99], v[136:137]
	v_pk_mul_f32 v[100:101], v[100:101], v[136:137]
	v_cvt_pk_bf16_f32 v110, v110, v111
	v_cvt_pk_bf16_f32 v111, v112, v113
	v_cvt_pk_bf16_f32 v112, v106, v107
	v_cvt_pk_bf16_f32 v113, v108, v109
	v_cvt_pk_bf16_f32 v102, v102, v103
	v_cvt_pk_bf16_f32 v103, v104, v105
	v_cvt_pk_bf16_f32 v104, v98, v99
	v_cvt_pk_bf16_f32 v105, v100, v101
	s_nop 1
	v_permlane16_swap_b32_e32 v110, v112
	v_permlane16_swap_b32_e32 v111, v113
	v_permlane16_swap_b32_e32 v102, v104
	v_permlane16_swap_b32_e32 v103, v105
	global_store_dwordx4 v[246:247], v[110:113], off
	global_store_dwordx4 v[246:247], v[102:105], off offset:64
	v_add_co_u32_e32 v246, vcc, 0x8000, v246
	s_nop 1
	v_addc_co_u32_e32 v247, vcc, 0, v247, vcc
	s_waitcnt vmcnt(9)
	v_add_f32_e32 v132, v218, v219
	v_add_f32_e32 v133, v220, v221
	v_add_f32_e32 v132, v132, v133
	v_mov_b32_e32 v133, v132
	v_mov_b32_e32 v134, v132
	s_nop 1
	v_permlane32_swap_b32_e32 v133, v134
	v_add_f32_e32 v132, v133, v134
	v_mov_b32_e32 v133, v132
	v_mov_b32_e32 v134, v132
	s_nop 1
	v_permlane16_swap_b32_e32 v133, v134
	v_add_f32_e32 v132, v133, v134
	v_fmaak_f32 v133, v132, v130, 0x3727c5ac
	v_rsq_f32_e32 v134, v133
	v_mul_f32_e32 v133, 0.5, v133
	s_nop 0
	v_mul_f32_e32 v132, v133, v134
	v_fma_f32 v132, -v132, v134, 0.5
	v_fma_f32 v136, v134, v132, v134
	v_mul_f32_e32 v136, 0x3d800000, v136
	v_mov_b32_e32 v137, v136
	v_pk_mul_f32 v[94:95], v[94:95], v[136:137]
	v_pk_mul_f32 v[96:97], v[96:97], v[136:137]
	v_pk_mul_f32 v[90:91], v[90:91], v[136:137]
	v_pk_mul_f32 v[92:93], v[92:93], v[136:137]
	v_pk_mul_f32 v[86:87], v[86:87], v[136:137]
	v_pk_mul_f32 v[88:89], v[88:89], v[136:137]
	v_pk_mul_f32 v[82:83], v[82:83], v[136:137]
	v_pk_mul_f32 v[84:85], v[84:85], v[136:137]
	v_cvt_pk_bf16_f32 v94, v94, v95
	v_cvt_pk_bf16_f32 v95, v96, v97
	v_cvt_pk_bf16_f32 v96, v90, v91
	v_cvt_pk_bf16_f32 v97, v92, v93
	v_cvt_pk_bf16_f32 v86, v86, v87
	v_cvt_pk_bf16_f32 v87, v88, v89
	v_cvt_pk_bf16_f32 v88, v82, v83
	v_cvt_pk_bf16_f32 v89, v84, v85
	s_nop 1
	v_permlane16_swap_b32_e32 v94, v96
	v_permlane16_swap_b32_e32 v95, v97
	v_permlane16_swap_b32_e32 v86, v88
	v_permlane16_swap_b32_e32 v87, v89
	global_store_dwordx4 v[246:247], v[94:97], off
	global_store_dwordx4 v[246:247], v[86:89], off offset:64
	v_add_co_u32_e32 v246, vcc, 0x8000, v246
	s_nop 1
	v_addc_co_u32_e32 v247, vcc, 0, v247, vcc
	s_waitcnt vmcnt(10)
	v_add_f32_e32 v132, v222, v223
	v_add_f32_e32 v133, v224, v225
	v_add_f32_e32 v132, v132, v133
	v_mov_b32_e32 v133, v132
	v_mov_b32_e32 v134, v132
	s_nop 1
	v_permlane32_swap_b32_e32 v133, v134
	v_add_f32_e32 v132, v133, v134
	v_mov_b32_e32 v133, v132
	v_mov_b32_e32 v134, v132
	s_nop 1
	v_permlane16_swap_b32_e32 v133, v134
	v_add_f32_e32 v132, v133, v134
	v_fmaak_f32 v133, v132, v130, 0x3727c5ac
	v_rsq_f32_e32 v134, v133
	v_mul_f32_e32 v133, 0.5, v133
	s_nop 0
	v_mul_f32_e32 v132, v133, v134
	v_fma_f32 v132, -v132, v134, 0.5
	v_fma_f32 v136, v134, v132, v134
	v_mul_f32_e32 v136, 0x3d800000, v136
	v_mov_b32_e32 v137, v136
	v_pk_mul_f32 v[78:79], v[78:79], v[136:137]
	v_pk_mul_f32 v[80:81], v[80:81], v[136:137]
	v_pk_mul_f32 v[74:75], v[74:75], v[136:137]
	v_pk_mul_f32 v[76:77], v[76:77], v[136:137]
	v_pk_mul_f32 v[70:71], v[70:71], v[136:137]
	v_pk_mul_f32 v[72:73], v[72:73], v[136:137]
	v_pk_mul_f32 v[66:67], v[66:67], v[136:137]
	v_pk_mul_f32 v[68:69], v[68:69], v[136:137]
	v_cvt_pk_bf16_f32 v78, v78, v79
	v_cvt_pk_bf16_f32 v79, v80, v81
	v_cvt_pk_bf16_f32 v80, v74, v75
	v_cvt_pk_bf16_f32 v81, v76, v77
	v_cvt_pk_bf16_f32 v70, v70, v71
	v_cvt_pk_bf16_f32 v71, v72, v73
	v_cvt_pk_bf16_f32 v72, v66, v67
	v_cvt_pk_bf16_f32 v73, v68, v69
	s_nop 1
	v_permlane16_swap_b32_e32 v78, v80
	v_permlane16_swap_b32_e32 v79, v81
	v_permlane16_swap_b32_e32 v70, v72
	v_permlane16_swap_b32_e32 v71, v73
	global_store_dwordx4 v[246:247], v[78:81], off
	global_store_dwordx4 v[246:247], v[70:73], off offset:64
	v_add_co_u32_e32 v246, vcc, 0x8000, v246
	s_nop 1
	v_addc_co_u32_e32 v247, vcc, 0, v247, vcc
	s_waitcnt vmcnt(11)
	v_add_f32_e32 v132, v226, v227
	v_add_f32_e32 v133, v228, v229
	v_add_f32_e32 v132, v132, v133
	v_mov_b32_e32 v133, v132
	v_mov_b32_e32 v134, v132
	s_nop 1
	v_permlane32_swap_b32_e32 v133, v134
	v_add_f32_e32 v132, v133, v134
	v_mov_b32_e32 v133, v132
	v_mov_b32_e32 v134, v132
	s_nop 1
	v_permlane16_swap_b32_e32 v133, v134
	v_add_f32_e32 v132, v133, v134
	v_fmaak_f32 v133, v132, v130, 0x3727c5ac
	v_rsq_f32_e32 v134, v133
	v_mul_f32_e32 v133, 0.5, v133
	s_nop 0
	v_mul_f32_e32 v132, v133, v134
	v_fma_f32 v132, -v132, v134, 0.5
	v_fma_f32 v136, v134, v132, v134
	v_mul_f32_e32 v136, 0x3d800000, v136
	v_mov_b32_e32 v137, v136
	v_pk_mul_f32 v[60:61], v[60:61], v[136:137]
	v_pk_mul_f32 v[62:63], v[62:63], v[136:137]
	v_pk_mul_f32 v[56:57], v[56:57], v[136:137]
	v_pk_mul_f32 v[58:59], v[58:59], v[136:137]
	v_pk_mul_f32 v[52:53], v[52:53], v[136:137]
	v_pk_mul_f32 v[54:55], v[54:55], v[136:137]
	v_pk_mul_f32 v[48:49], v[48:49], v[136:137]
	v_pk_mul_f32 v[50:51], v[50:51], v[136:137]
	v_cvt_pk_bf16_f32 v60, v60, v61
	v_cvt_pk_bf16_f32 v61, v62, v63
	v_cvt_pk_bf16_f32 v62, v56, v57
	v_cvt_pk_bf16_f32 v63, v58, v59
	v_cvt_pk_bf16_f32 v52, v52, v53
	v_cvt_pk_bf16_f32 v53, v54, v55
	v_cvt_pk_bf16_f32 v54, v48, v49
	v_cvt_pk_bf16_f32 v55, v50, v51
	s_nop 1
	v_permlane16_swap_b32_e32 v60, v62
	v_permlane16_swap_b32_e32 v61, v63
	v_permlane16_swap_b32_e32 v52, v54
	v_permlane16_swap_b32_e32 v53, v55
	global_store_dwordx4 v[246:247], v[60:63], off
	global_store_dwordx4 v[246:247], v[52:55], off offset:64
	v_add_co_u32_e32 v246, vcc, 0x8000, v246
	s_nop 1
	v_addc_co_u32_e32 v247, vcc, 0, v247, vcc
	s_waitcnt vmcnt(12)
	v_add_f32_e32 v132, v230, v231
	v_add_f32_e32 v133, v232, v233
	v_add_f32_e32 v132, v132, v133
	v_mov_b32_e32 v133, v132
	v_mov_b32_e32 v134, v132
	s_nop 1
	v_permlane32_swap_b32_e32 v133, v134
	v_add_f32_e32 v132, v133, v134
	v_mov_b32_e32 v133, v132
	v_mov_b32_e32 v134, v132
	s_nop 1
	v_permlane16_swap_b32_e32 v133, v134
	v_add_f32_e32 v132, v133, v134
	v_fmaak_f32 v133, v132, v130, 0x3727c5ac
	v_rsq_f32_e32 v134, v133
	v_mul_f32_e32 v133, 0.5, v133
	s_nop 0
	v_mul_f32_e32 v132, v133, v134
	v_fma_f32 v132, -v132, v134, 0.5
	v_fma_f32 v136, v134, v132, v134
	v_mul_f32_e32 v136, 0x3d800000, v136
	v_mov_b32_e32 v137, v136
	v_pk_mul_f32 v[44:45], v[44:45], v[136:137]
	v_pk_mul_f32 v[46:47], v[46:47], v[136:137]
	v_pk_mul_f32 v[40:41], v[40:41], v[136:137]
	v_pk_mul_f32 v[42:43], v[42:43], v[136:137]
	v_pk_mul_f32 v[36:37], v[36:37], v[136:137]
	v_pk_mul_f32 v[38:39], v[38:39], v[136:137]
	v_pk_mul_f32 v[32:33], v[32:33], v[136:137]
	v_pk_mul_f32 v[34:35], v[34:35], v[136:137]
	v_cvt_pk_bf16_f32 v44, v44, v45
	v_cvt_pk_bf16_f32 v45, v46, v47
	v_cvt_pk_bf16_f32 v46, v40, v41
	v_cvt_pk_bf16_f32 v47, v42, v43
	v_cvt_pk_bf16_f32 v36, v36, v37
	v_cvt_pk_bf16_f32 v37, v38, v39
	v_cvt_pk_bf16_f32 v38, v32, v33
	v_cvt_pk_bf16_f32 v39, v34, v35
	s_nop 1
	v_permlane16_swap_b32_e32 v44, v46
	v_permlane16_swap_b32_e32 v45, v47
	v_permlane16_swap_b32_e32 v36, v38
	v_permlane16_swap_b32_e32 v37, v39
	global_store_dwordx4 v[246:247], v[44:47], off
	global_store_dwordx4 v[246:247], v[36:39], off offset:64
	v_add_co_u32_e32 v246, vcc, 0x8000, v246
	s_nop 1
	v_addc_co_u32_e32 v247, vcc, 0, v247, vcc
	s_waitcnt vmcnt(13)
	v_add_f32_e32 v132, v234, v235
	v_add_f32_e32 v133, v236, v237
	v_add_f32_e32 v132, v132, v133
	v_mov_b32_e32 v133, v132
	v_mov_b32_e32 v134, v132
	s_nop 1
	v_permlane32_swap_b32_e32 v133, v134
	v_add_f32_e32 v132, v133, v134
	v_mov_b32_e32 v133, v132
	v_mov_b32_e32 v134, v132
	s_nop 1
	v_permlane16_swap_b32_e32 v133, v134
	v_add_f32_e32 v132, v133, v134
	v_fmaak_f32 v133, v132, v130, 0x3727c5ac
	v_rsq_f32_e32 v134, v133
	v_mul_f32_e32 v133, 0.5, v133
	s_nop 0
	v_mul_f32_e32 v132, v133, v134
	v_fma_f32 v132, -v132, v134, 0.5
	v_fma_f32 v136, v134, v132, v134
	v_mul_f32_e32 v136, 0x3d800000, v136
	v_mov_b32_e32 v137, v136
	v_pk_mul_f32 v[24:25], v[24:25], v[136:137]
	v_pk_mul_f32 v[26:27], v[26:27], v[136:137]
	v_pk_mul_f32 v[20:21], v[20:21], v[136:137]
	v_pk_mul_f32 v[22:23], v[22:23], v[136:137]
	v_pk_mul_f32 v[16:17], v[16:17], v[136:137]
	v_pk_mul_f32 v[18:19], v[18:19], v[136:137]
	v_pk_mul_f32 v[12:13], v[12:13], v[136:137]
	v_pk_mul_f32 v[14:15], v[14:15], v[136:137]
	v_cvt_pk_bf16_f32 v24, v24, v25
	v_cvt_pk_bf16_f32 v25, v26, v27
	v_cvt_pk_bf16_f32 v26, v20, v21
	v_cvt_pk_bf16_f32 v27, v22, v23
	v_cvt_pk_bf16_f32 v16, v16, v17
	v_cvt_pk_bf16_f32 v17, v18, v19
	v_cvt_pk_bf16_f32 v18, v12, v13
	v_cvt_pk_bf16_f32 v19, v14, v15
	s_nop 1
	v_permlane16_swap_b32_e32 v24, v26
	v_permlane16_swap_b32_e32 v25, v27
	v_permlane16_swap_b32_e32 v16, v18
	v_permlane16_swap_b32_e32 v17, v19
	global_store_dwordx4 v[246:247], v[24:27], off
	global_store_dwordx4 v[246:247], v[16:19], off offset:64
	v_add_co_u32_e32 v246, vcc, 0x8000, v246
	s_nop 1
	v_addc_co_u32_e32 v247, vcc, 0, v247, vcc
	s_waitcnt vmcnt(14)
	v_add_f32_e32 v132, v252, v253
	v_add_f32_e32 v133, v254, v255
	v_add_f32_e32 v132, v132, v133
	v_mov_b32_e32 v133, v132
	v_mov_b32_e32 v134, v132
	s_nop 1
	v_permlane32_swap_b32_e32 v133, v134
	v_add_f32_e32 v132, v133, v134
	v_mov_b32_e32 v133, v132
	v_mov_b32_e32 v134, v132
	s_nop 1
	v_permlane16_swap_b32_e32 v133, v134
	v_add_f32_e32 v132, v133, v134
	v_fmaak_f32 v133, v132, v130, 0x3727c5ac
	v_rsq_f32_e32 v134, v133
	v_mul_f32_e32 v133, 0.5, v133
	s_nop 0
	v_mul_f32_e32 v132, v133, v134
	v_fma_f32 v132, -v132, v134, 0.5
	v_fma_f32 v136, v134, v132, v134
	v_mul_f32_e32 v136, 0x3d800000, v136
	v_mov_b32_e32 v137, v136
	v_pk_mul_f32 v[8:9], v[8:9], v[136:137]
	v_pk_mul_f32 v[10:11], v[10:11], v[136:137]
	v_pk_mul_f32 v[4:5], v[4:5], v[136:137]
	v_pk_mul_f32 v[6:7], v[6:7], v[136:137]
	v_pk_mul_f32 v[0:1], v[0:1], v[136:137]
	v_pk_mul_f32 v[2:3], v[2:3], v[136:137]
	v_pk_mul_f32 v[28:29], v[28:29], v[136:137]
	v_pk_mul_f32 v[30:31], v[30:31], v[136:137]
	v_cvt_pk_bf16_f32 v8, v8, v9
	v_cvt_pk_bf16_f32 v9, v10, v11
	v_cvt_pk_bf16_f32 v10, v4, v5
	v_cvt_pk_bf16_f32 v11, v6, v7
	v_cvt_pk_bf16_f32 v0, v0, v1
	v_cvt_pk_bf16_f32 v1, v2, v3
	v_cvt_pk_bf16_f32 v2, v28, v29
	v_cvt_pk_bf16_f32 v3, v30, v31
	s_nop 1
	v_permlane16_swap_b32_e32 v8, v10
	v_permlane16_swap_b32_e32 v9, v11
	v_permlane16_swap_b32_e32 v0, v2
	v_permlane16_swap_b32_e32 v1, v3
	global_store_dwordx4 v[246:247], v[8:11], off
	global_store_dwordx4 v[246:247], v[0:3], off offset:64
	v_mov_b32_e32 v90, v166
	s_waitcnt vmcnt(0)
	s_barrier
	s_add_i32 s0, s26, s44
	v_ashrrev_i32_e32 v32, 31, v90
	s_ashr_i32 s1, s0, 31
	s_ashr_i32 s27, s26, 31
	v_lshrrev_b32_e32 v32, 27, v32
	s_lshl_b64 s[0:1], s[0:1], 20
	s_lshl_b64 s[24:25], s[26:27], 12
	s_lshl_b32 s27, s65, 8
	v_readlane_b32 s2, v241, 44
	v_add_u32_e32 v32, v90, v32
	s_add_u32 s0, s2, s0
	v_readlane_b32 s2, v241, 45
	v_ashrrev_i32_e32 v66, 5, v32
	v_and_b32_e32 v32, 0xffffffe0, v32
	s_addc_u32 s1, s2, s1
	v_sub_u32_e32 v93, v90, v32
	s_add_u32 s0, s0, s84
	v_ashrrev_i32_e32 v67, 31, v66
	v_lshlrev_b32_e32 v34, 3, v93
	s_addc_u32 s1, s1, 0
	v_lshlrev_b64 v[68:69], 12, v[66:67]
	v_ashrrev_i32_e32 v35, 31, v34
	v_lshl_add_u64 v[32:33], s[0:1], 0, v[68:69]
	v_lshlrev_b64 v[70:71], 1, v[34:35]
	v_lshl_add_u64 v[36:37], v[32:33], 0, v[70:71]
	v_add_u32_e32 v32, 0x200, v90
	v_ashrrev_i32_e32 v33, 31, v32
	v_lshrrev_b32_e32 v33, 27, v33
	v_add_u32_e32 v33, v32, v33
	v_ashrrev_i32_e32 v72, 5, v33
	v_and_b32_e32 v33, 0xffffffe0, v33
	v_sub_u32_e32 v67, v32, v33
	v_ashrrev_i32_e32 v73, 31, v72
	v_lshlrev_b32_e32 v34, 3, v67
	v_lshlrev_b64 v[74:75], 12, v[72:73]
	v_ashrrev_i32_e32 v35, 31, v34
	v_lshl_add_u64 v[32:33], s[0:1], 0, v[74:75]
	v_lshlrev_b64 v[76:77], 1, v[34:35]
	v_lshl_add_u64 v[44:45], v[32:33], 0, v[76:77]
	v_add_u32_e32 v32, 0x400, v90
	v_ashrrev_i32_e32 v33, 31, v32
	v_lshrrev_b32_e32 v33, 27, v33
	v_add_u32_e32 v33, v32, v33
	v_ashrrev_i32_e32 v78, 5, v33
	v_and_b32_e32 v33, 0xffffffe0, v33
	v_sub_u32_e32 v73, v32, v33
	v_ashrrev_i32_e32 v79, 31, v78
	v_lshlrev_b32_e32 v34, 3, v73
	v_lshlrev_b64 v[80:81], 12, v[78:79]
	v_ashrrev_i32_e32 v35, 31, v34
	v_lshl_add_u64 v[32:33], s[0:1], 0, v[80:81]
	v_lshlrev_b64 v[82:83], 1, v[34:35]
	v_lshl_add_u64 v[52:53], v[32:33], 0, v[82:83]
	v_add_u32_e32 v32, 0x600, v90
	v_ashrrev_i32_e32 v33, 31, v32
	v_and_b32_e32 v91, 15, v90
	v_ashrrev_i32_e32 v0, 2, v90
	v_lshrrev_b32_e32 v33, 27, v33
	v_and_b32_e32 v0, -16, v0
	v_or_b32_e32 v2, s27, v91
	v_add_u32_e32 v33, v32, v33
	v_ashrrev_i32_e32 v1, 31, v0
	v_or_b32_e32 v2, s24, v2
	v_mov_b32_e32 v3, s25
	v_ashrrev_i32_e32 v84, 5, v33
	v_and_b32_e32 v33, 0xffffffe0, v33
	v_lshl_add_u64 v[0:1], v[2:3], 0, v[0:1]
	v_sub_u32_e32 v79, v32, v33
	v_lshlrev_b64 v[138:139], 11, v[0:1]
	v_ashrrev_i32_e32 v85, 31, v84
	v_lshlrev_b32_e32 v34, 3, v79
	v_bfe_u32 v92, v90, 4, 2
	v_lshl_add_u64 v[0:1], s[18:19], 0, v[138:139]
	v_lshlrev_b64 v[86:87], 12, v[84:85]
	v_ashrrev_i32_e32 v35, 31, v34
	v_lshl_add_u64 v[0:1], v[0:1], 0, s[84:85]
	v_lshlrev_b32_e32 v64, 4, v92
	v_lshl_add_u64 v[32:33], s[0:1], 0, v[86:87]
	v_lshlrev_b64 v[88:89], 1, v[34:35]
	v_lshl_add_u64 v[28:29], v[0:1], 0, v[64:65]
	v_lshl_add_u64 v[60:61], v[32:33], 0, v[88:89]
	global_load_dwordx4 v[0:3], v[28:29], off
	global_load_dwordx4 v[4:7], v[28:29], off offset:64
	global_load_dwordx4 v[8:11], v[28:29], off offset:128
	global_load_dwordx4 v[12:15], v[28:29], off offset:192
	global_load_dwordx4 v[16:19], v[28:29], off offset:256
	global_load_dwordx4 v[20:23], v[28:29], off offset:320
	global_load_dwordx4 v[24:27], v[28:29], off offset:384
	s_nop 0
	global_load_dwordx4 v[28:31], v[28:29], off offset:448
	s_nop 0
	global_load_dwordx4 v[32:35], v[36:37], off
	s_nop 0
	global_load_dwordx4 v[36:39], v[36:37], off offset:2048
	s_nop 0
	global_load_dwordx4 v[40:43], v[44:45], off
	s_nop 0
	global_load_dwordx4 v[44:47], v[44:45], off offset:2048
	s_nop 0
	global_load_dwordx4 v[48:51], v[52:53], off
	s_nop 0
	global_load_dwordx4 v[52:55], v[52:53], off offset:2048
	s_nop 0
	global_load_dwordx4 v[56:59], v[60:61], off
	s_nop 0
	global_load_dwordx4 v[60:63], v[60:61], off offset:2048
	s_movk_i32 s2, 0x210
	v_mul_lo_u32 v151, v66, s2
	v_cmp_lt_i32_e32 vcc, v157, v168
	v_lshlrev_b32_e32 v160, 4, v73
	v_lshl_add_u32 v73, v66, 4, v151
	v_cndmask_b32_e32 v66, v155, v157, vcc
	v_cmp_lt_i32_e32 vcc, v169, v168
	v_lshlrev_b32_e32 v148, 2, v66
	v_lshlrev_b32_e32 v150, 2, v92
	v_cndmask_b32_e32 v66, v155, v169, vcc
	v_lshlrev_b32_e32 v149, 2, v66
	v_bfe_u32 v66, v90, 2, 2
	s_add_i32 s28, s73, s26
	v_or_b32_e32 v66, v150, v66
	s_ashr_i32 s29, s28, 31
	v_lshlrev_b32_e32 v158, 4, v67
	v_mul_u32_u24_e32 v66, 0x220, v66
	v_lshlrev_b32_e32 v67, 3, v90
	s_lshl_b64 s[28:29], s[28:29], 20
	v_and_or_b32 v163, v67, 24, v66
	v_lshl_add_u64 v[66:67], s[28:29], 0, v[86:87]
	v_or_b32_e32 v66, s40, v66
	v_lshl_add_u64 v[66:67], v[66:67], 0, v[88:89]
	v_lshl_add_u64 v[140:141], s[68:69], 0, v[66:67]
	v_lshl_add_u64 v[66:67], s[28:29], 0, v[80:81]
	v_or_b32_e32 v66, s40, v66
	v_lshl_add_u64 v[66:67], v[66:67], 0, v[82:83]
	v_lshl_add_u64 v[142:143], s[68:69], 0, v[66:67]
	v_lshl_add_u64 v[66:67], s[28:29], 0, v[74:75]
	v_or_b32_e32 v66, s40, v66
	v_lshl_add_u64 v[66:67], v[66:67], 0, v[76:77]
	v_lshl_add_u64 v[144:145], s[68:69], 0, v[66:67]
	v_lshl_add_u64 v[66:67], s[28:29], 0, v[68:69]
	v_mul_lo_u32 v153, v72, s2
	v_mul_lo_u32 v159, v78, s2
	v_mul_lo_u32 v161, v84, s2
	v_or_b32_e32 v66, s40, v66
	v_lshlrev_b32_e32 v152, 4, v93
	v_lshlrev_b32_e32 v162, 4, v79
	v_lshl_add_u32 v72, v72, 4, v153
	v_lshl_add_u32 v78, v78, 4, v159
	v_lshl_add_u32 v79, v84, 4, v161
	v_mul_u32_u24_e32 v84, 0x210, v91
	v_lshl_add_u64 v[66:67], v[66:67], 0, v[70:71]
	v_mov_b32_e32 v130, 0
	v_lshl_add_u64 v[146:147], s[68:69], 0, v[66:67]
	v_mov_b32_e32 v131, 0xff800000
	s_mov_b64 s[30:31], 0
	v_add_u32_e32 v164, v73, v152
	v_add_u32_e32 v165, v72, v158
	v_add_u32_e32 v197, v78, v160
	v_add_u32_e32 v198, v79, v162
	v_add_u32_e32 v199, v84, v64
	v_mov_b32_e32 v98, 0
	v_mov_b32_e32 v99, v130
	v_mov_b32_e32 v100, v130
	v_mov_b32_e32 v101, v130
	v_mov_b32_e32 v102, 0
	v_mov_b32_e32 v103, v130
	v_mov_b32_e32 v104, v130
	v_mov_b32_e32 v105, v130
	v_mov_b32_e32 v90, 0
	v_mov_b32_e32 v91, v130
	v_mov_b32_e32 v92, v130
	v_mov_b32_e32 v93, v130
	v_mov_b32_e32 v94, 0
	v_mov_b32_e32 v95, v130
	v_mov_b32_e32 v96, v130
	v_mov_b32_e32 v97, v130
	v_mov_b32_e32 v78, 0
	v_mov_b32_e32 v79, v130
	v_mov_b32_e32 v80, v130
	v_mov_b32_e32 v81, v130
	v_mov_b32_e32 v86, 0
	v_mov_b32_e32 v87, v130
	v_mov_b32_e32 v88, v130
	v_mov_b32_e32 v89, v130
	v_mov_b32_e32 v82, 0
	v_mov_b32_e32 v83, v130
	v_mov_b32_e32 v84, v130
	v_mov_b32_e32 v85, v130
	v_mov_b32_e32 v106, 0
	v_mov_b32_e32 v107, v130
	v_mov_b32_e32 v108, v130
	v_mov_b32_e32 v109, v130
	v_mov_b32_e32 v110, 0
	v_mov_b32_e32 v111, v130
	v_mov_b32_e32 v112, v130
	v_mov_b32_e32 v113, v130
	v_mov_b32_e32 v114, 0
	v_mov_b32_e32 v115, v130
	v_mov_b32_e32 v116, v130
	v_mov_b32_e32 v117, v130
	v_mov_b32_e32 v66, 0
	v_mov_b32_e32 v67, v130
	v_mov_b32_e32 v68, v130
	v_mov_b32_e32 v69, v130
	v_mov_b32_e32 v74, 0
	v_mov_b32_e32 v75, v130
	v_mov_b32_e32 v76, v130
	v_mov_b32_e32 v77, v130
	v_mov_b32_e32 v118, 0
	v_mov_b32_e32 v119, v130
	v_mov_b32_e32 v120, v130
	v_mov_b32_e32 v121, v130
	v_mov_b32_e32 v122, 0
	v_mov_b32_e32 v123, v130
	v_mov_b32_e32 v124, v130
	v_mov_b32_e32 v125, v130
	v_mov_b32_e32 v126, 0
	v_mov_b32_e32 v127, v130
	v_mov_b32_e32 v128, v130
	v_mov_b32_e32 v129, v130
	v_mov_b32_e32 v70, 0
	v_mov_b32_e32 v71, v130
	v_mov_b32_e32 v72, v130
	v_mov_b32_e32 v73, v130

.LBB0_1494:
	v_lshrrev_b32_e32 v210, 1, v166
	v_and_b32_e32 v210, 0x80, v210
	v_and_b32_e32 v211, 15, v166
	v_or_b32_e32 v210, v210, v211
	v_and_b32_e32 v211, 0xc0, v166
	v_and_b32_e32 v212, 16, v166
	v_lshrrev_b32_e32 v213, 2, v166
	v_and_b32_e32 v213, 8, v213
	v_or_b32_e32 v212, v212, v213
	v_lshlrev_b32_e32 v213, 10, v210
	v_add3_u32 v213, v213, v211, v212
	v_lshlrev_b32_e32 v213, 1, v213
	v_lshl_add_u32 v213, s30, 19, v213
	v_lshl_add_u32 v213, s40, 9, v213
	v_lshlrev_b32_e32 v214, 6, v210
	v_lshrrev_b32_e32 v215, 4, v211
	v_add_u32_e32 v214, v214, v215
	v_lshl_add_u32 v214, s30, 14, v214
	v_lshl_add_u32 v214, s40, 4, v214
	v_lshrrev_b32_e32 v216, 2, v166
	v_and_b32_e32 v216, 12, v216
	v_add_u32_e32 v216, v216, v211
	v_lshl_add_u32 v216, s40, 8, v216
	v_lshlrev_b32_e32 v216, 2, v216
	s_add_i32 s64, s64, 1
	s_lshl_b64 s[26:27], s[30:31], 20
	s_add_u32 s1, s38, s26
	s_addc_u32 s25, s39, s27
	s_lshl_b32 s26, s40, 8
	s_ashr_i32 s27, s26, 31
	s_lshl_b64 s[26:27], s[26:27], 2
	s_add_u32 s30, s1, s26
	s_mov_b32 s1, 0x3fff80
	s_addc_u32 s31, s25, s27
	v_readlane_b32 s26, v241, 46
	v_readlane_b32 s27, v241, 47
	v_mov_b32_e32 v217, 0
	s_nop 1
	v_lshl_add_u64 v[216:217], v[216:217], 0, s[26:27]
	global_load_dwordx4 v[218:221], v[216:217], off
	global_load_dwordx4 v[222:225], v[216:217], off offset:64
	global_load_dwordx4 v[226:229], v[216:217], off offset:128
	global_load_dwordx4 v[230:233], v[216:217], off offset:192
	v_mov_b32_e32 v234, v213
	v_mov_b32_e32 v235, 0
	v_lshl_add_u64 v[234:235], v[234:235], 0, s[14:15]
	s_add_u32 s26, s92, 0x35624900
	s_addc_u32 s27, s93, 0
	v_mov_b32_e32 v236, v214
	v_mov_b32_e32 v237, 0
	v_lshl_add_u64 v[236:237], v[236:237], 0, s[26:27]
	v_lshrrev_b32_e32 v250, 1, v166
	v_and_b32_e32 v250, 0x80, v250
	v_and_b32_e32 v251, 15, v166
	v_or_b32_e32 v250, v250, v251
	v_lshrrev_b32_e32 v251, 2, v166
	v_and_b32_e32 v251, 12, v251
	v_and_b32_e32 v252, 0xc0, v166
	v_or_b32_e32 v251, v251, v252
	v_lshl_or_b32 v250, v250, 10, v251
	v_mov_b32_e32 v251, 0
	v_lshl_add_u64 v[246:247], v[250:251], 2, s[30:31]
	v_mov_b32_e32 v248, v246
	v_mov_b32_e32 v249, v247
	global_load_dwordx4 v[130:133], v[246:247], off
	global_load_dwordx4 v[134:137], v[246:247], off offset:64
	global_load_dwordx4 v[138:141], v[246:247], off offset:128
	global_load_dwordx4 v[142:145], v[246:247], off offset:192
	v_add_co_u32_e32 v246, vcc, 0x10000, v246
	s_nop 1
	v_addc_co_u32_e32 v247, vcc, 0, v247, vcc
	global_load_dwordx4 v[146:149], v[246:247], off
	global_load_dwordx4 v[150:153], v[246:247], off offset:64
	global_load_dwordx4 v[202:205], v[246:247], off offset:128
	global_load_dwordx4 v[206:209], v[246:247], off offset:192
	v_add_co_u32_e32 v246, vcc, 0x10000, v246
	s_nop 1
	v_addc_co_u32_e32 v247, vcc, 0, v247, vcc
	s_waitcnt vmcnt(4)
	v_pk_add_f32 v[126:127], v[126:127], v[130:131]
	v_pk_add_f32 v[128:129], v[128:129], v[132:133]
	v_pk_add_f32 v[122:123], v[122:123], v[134:135]
	v_pk_add_f32 v[124:125], v[124:125], v[136:137]
	v_pk_add_f32 v[118:119], v[118:119], v[138:139]
	v_pk_add_f32 v[120:121], v[120:121], v[140:141]
	v_pk_add_f32 v[114:115], v[114:115], v[142:143]
	v_pk_add_f32 v[116:117], v[116:117], v[144:145]
	global_store_dwordx4 v[248:249], v[126:129], off
	global_store_dwordx4 v[248:249], v[122:125], off offset:64
	global_store_dwordx4 v[248:249], v[118:121], off offset:128
	global_store_dwordx4 v[248:249], v[114:117], off offset:192
	v_add_co_u32_e32 v248, vcc, 0x10000, v248
	s_nop 1
	v_addc_co_u32_e32 v249, vcc, 0, v249, vcc
	v_pk_mul_f32 v[238:239], v[126:127], v[218:219]
	v_pk_mul_f32 v[250:251], v[128:129], v[220:221]
	v_cvt_pk_bf16_f32 v252, v238, v239
	v_cvt_pk_bf16_f32 v253, v250, v251
	v_pk_mul_f32 v[238:239], v[122:123], v[222:223]
	v_pk_mul_f32 v[250:251], v[124:125], v[224:225]
	v_cvt_pk_bf16_f32 v254, v238, v239
	v_cvt_pk_bf16_f32 v255, v250, v251
	s_nop 1
	v_permlane16_swap_b32_e32 v252, v254
	v_permlane16_swap_b32_e32 v253, v255
	global_store_dwordx4 v[234:235], v[252:255], off
	v_pk_mul_f32 v[238:239], v[118:119], v[226:227]
	v_pk_mul_f32 v[250:251], v[120:121], v[228:229]
	v_cvt_pk_bf16_f32 v252, v238, v239
	v_cvt_pk_bf16_f32 v253, v250, v251
	v_pk_mul_f32 v[238:239], v[114:115], v[230:231]
	v_pk_mul_f32 v[250:251], v[116:117], v[232:233]
	v_cvt_pk_bf16_f32 v254, v238, v239
	v_cvt_pk_bf16_f32 v255, v250, v251
	s_nop 1
	v_permlane16_swap_b32_e32 v252, v254
	v_permlane16_swap_b32_e32 v253, v255
	global_store_dwordx4 v[234:235], v[252:255], off offset:64
	v_pk_mul_f32 v[210:211], v[126:127], v[126:127]
	v_pk_fma_f32 v[210:211], v[128:129], v[128:129], v[210:211]
	v_pk_fma_f32 v[210:211], v[122:123], v[122:123], v[210:211]
	v_pk_fma_f32 v[210:211], v[124:125], v[124:125], v[210:211]
	v_pk_fma_f32 v[210:211], v[118:119], v[118:119], v[210:211]
	v_pk_fma_f32 v[210:211], v[120:121], v[120:121], v[210:211]
	v_pk_fma_f32 v[210:211], v[114:115], v[114:115], v[210:211]
	v_pk_fma_f32 v[210:211], v[116:117], v[116:117], v[210:211]
	v_add_f32_e32 v212, v210, v211
	v_mov_b32_e32 v213, v212
	v_mov_b32_e32 v214, v212
	s_nop 1
	v_permlane32_swap_b32_e32 v213, v214
	v_add_f32_e32 v212, v213, v214
	v_mov_b32_e32 v213, v212
	v_mov_b32_e32 v214, v212
	s_nop 1
	v_permlane16_swap_b32_e32 v213, v214
	v_add_f32_e32 v212, v213, v214
	s_mov_b64 exec, 0xffff
	global_store_dword v[236:237], v212, off
	s_mov_b64 exec, -1
	v_add_co_u32_e32 v234, vcc, 0x8000, v234
	s_nop 1
	v_addc_co_u32_e32 v235, vcc, 0, v235, vcc
	v_add_co_u32_e32 v236, vcc, 0x400, v236
	s_nop 1
	v_addc_co_u32_e32 v237, vcc, 0, v237, vcc
	global_load_dwordx4 v[130:133], v[246:247], off
	global_load_dwordx4 v[134:137], v[246:247], off offset:64
	global_load_dwordx4 v[138:141], v[246:247], off offset:128
	global_load_dwordx4 v[142:145], v[246:247], off offset:192
	v_add_co_u32_e32 v246, vcc, 0x10000, v246
	s_nop 1
	v_addc_co_u32_e32 v247, vcc, 0, v247, vcc
	global_load_dwordx4 v[126:129], v[246:247], off
	global_load_dwordx4 v[122:125], v[246:247], off offset:64
	global_load_dwordx4 v[118:121], v[246:247], off offset:128
	global_load_dwordx4 v[114:117], v[246:247], off offset:192
	v_add_co_u32_e32 v246, vcc, 0x10000, v246
	s_nop 1
	v_addc_co_u32_e32 v247, vcc, 0, v247, vcc
	s_waitcnt vmcnt(15)
	v_pk_add_f32 v[110:111], v[110:111], v[146:147]
	v_pk_add_f32 v[112:113], v[112:113], v[148:149]
	v_pk_add_f32 v[106:107], v[106:107], v[150:151]
	v_pk_add_f32 v[108:109], v[108:109], v[152:153]
	v_pk_add_f32 v[102:103], v[102:103], v[202:203]
	v_pk_add_f32 v[104:105], v[104:105], v[204:205]
	v_pk_add_f32 v[98:99], v[98:99], v[206:207]
	v_pk_add_f32 v[100:101], v[100:101], v[208:209]
	global_store_dwordx4 v[248:249], v[110:113], off
	global_store_dwordx4 v[248:249], v[106:109], off offset:64
	global_store_dwordx4 v[248:249], v[102:105], off offset:128
	global_store_dwordx4 v[248:249], v[98:101], off offset:192
	v_add_co_u32_e32 v248, vcc, 0x10000, v248
	s_nop 1
	v_addc_co_u32_e32 v249, vcc, 0, v249, vcc
	v_pk_mul_f32 v[238:239], v[110:111], v[218:219]
	v_pk_mul_f32 v[250:251], v[112:113], v[220:221]
	v_cvt_pk_bf16_f32 v252, v238, v239
	v_cvt_pk_bf16_f32 v253, v250, v251
	v_pk_mul_f32 v[238:239], v[106:107], v[222:223]
	v_pk_mul_f32 v[250:251], v[108:109], v[224:225]
	v_cvt_pk_bf16_f32 v254, v238, v239
	v_cvt_pk_bf16_f32 v255, v250, v251
	s_nop 1
	v_permlane16_swap_b32_e32 v252, v254
	v_permlane16_swap_b32_e32 v253, v255
	global_store_dwordx4 v[234:235], v[252:255], off
	v_pk_mul_f32 v[238:239], v[102:103], v[226:227]
	v_pk_mul_f32 v[250:251], v[104:105], v[228:229]
	v_cvt_pk_bf16_f32 v252, v238, v239
	v_cvt_pk_bf16_f32 v253, v250, v251
	v_pk_mul_f32 v[238:239], v[98:99], v[230:231]
	v_pk_mul_f32 v[250:251], v[100:101], v[232:233]
	v_cvt_pk_bf16_f32 v254, v238, v239
	v_cvt_pk_bf16_f32 v255, v250, v251
	s_nop 1
	v_permlane16_swap_b32_e32 v252, v254
	v_permlane16_swap_b32_e32 v253, v255
	global_store_dwordx4 v[234:235], v[252:255], off offset:64
	v_pk_mul_f32 v[210:211], v[110:111], v[110:111]
	v_pk_fma_f32 v[210:211], v[112:113], v[112:113], v[210:211]
	v_pk_fma_f32 v[210:211], v[106:107], v[106:107], v[210:211]
	v_pk_fma_f32 v[210:211], v[108:109], v[108:109], v[210:211]
	v_pk_fma_f32 v[210:211], v[102:103], v[102:103], v[210:211]
	v_pk_fma_f32 v[210:211], v[104:105], v[104:105], v[210:211]
	v_pk_fma_f32 v[210:211], v[98:99], v[98:99], v[210:211]
	v_pk_fma_f32 v[210:211], v[100:101], v[100:101], v[210:211]
	v_add_f32_e32 v212, v210, v211
	v_mov_b32_e32 v213, v212
	v_mov_b32_e32 v214, v212
	s_nop 1
	v_permlane32_swap_b32_e32 v213, v214
	v_add_f32_e32 v212, v213, v214
	v_mov_b32_e32 v213, v212
	v_mov_b32_e32 v214, v212
	s_nop 1
	v_permlane16_swap_b32_e32 v213, v214
	v_add_f32_e32 v212, v213, v214
	s_mov_b64 exec, 0xffff
	global_store_dword v[236:237], v212, off
	s_mov_b64 exec, -1
	v_add_co_u32_e32 v234, vcc, 0x8000, v234
	s_nop 1
	v_addc_co_u32_e32 v235, vcc, 0, v235, vcc
	v_add_co_u32_e32 v236, vcc, 0x400, v236
	s_nop 1
	v_addc_co_u32_e32 v237, vcc, 0, v237, vcc
	global_load_dwordx4 v[146:149], v[246:247], off
	global_load_dwordx4 v[150:153], v[246:247], off offset:64
	global_load_dwordx4 v[202:205], v[246:247], off offset:128
	global_load_dwordx4 v[206:209], v[246:247], off offset:192
	v_add_co_u32_e32 v246, vcc, 0x10000, v246
	s_nop 1
	v_addc_co_u32_e32 v247, vcc, 0, v247, vcc
	global_load_dwordx4 v[110:113], v[246:247], off
	global_load_dwordx4 v[106:109], v[246:247], off offset:64
	global_load_dwordx4 v[102:105], v[246:247], off offset:128
	global_load_dwordx4 v[98:101], v[246:247], off offset:192
	v_add_co_u32_e32 v246, vcc, 0x10000, v246
	s_nop 1
	v_addc_co_u32_e32 v247, vcc, 0, v247, vcc
	s_waitcnt vmcnt(19)
	v_pk_add_f32 v[94:95], v[94:95], v[130:131]
	v_pk_add_f32 v[96:97], v[96:97], v[132:133]
	v_pk_add_f32 v[90:91], v[90:91], v[134:135]
	v_pk_add_f32 v[92:93], v[92:93], v[136:137]
	v_pk_add_f32 v[86:87], v[86:87], v[138:139]
	v_pk_add_f32 v[88:89], v[88:89], v[140:141]
	v_pk_add_f32 v[82:83], v[82:83], v[142:143]
	v_pk_add_f32 v[84:85], v[84:85], v[144:145]
	global_store_dwordx4 v[248:249], v[94:97], off
	global_store_dwordx4 v[248:249], v[90:93], off offset:64
	global_store_dwordx4 v[248:249], v[86:89], off offset:128
	global_store_dwordx4 v[248:249], v[82:85], off offset:192
	v_add_co_u32_e32 v248, vcc, 0x10000, v248
	s_nop 1
	v_addc_co_u32_e32 v249, vcc, 0, v249, vcc
	v_pk_mul_f32 v[238:239], v[94:95], v[218:219]
	v_pk_mul_f32 v[250:251], v[96:97], v[220:221]
	v_cvt_pk_bf16_f32 v252, v238, v239
	v_cvt_pk_bf16_f32 v253, v250, v251
	v_pk_mul_f32 v[238:239], v[90:91], v[222:223]
	v_pk_mul_f32 v[250:251], v[92:93], v[224:225]
	v_cvt_pk_bf16_f32 v254, v238, v239
	v_cvt_pk_bf16_f32 v255, v250, v251
	s_nop 1
	v_permlane16_swap_b32_e32 v252, v254
	v_permlane16_swap_b32_e32 v253, v255
	global_store_dwordx4 v[234:235], v[252:255], off
	v_pk_mul_f32 v[238:239], v[86:87], v[226:227]
	v_pk_mul_f32 v[250:251], v[88:89], v[228:229]
	v_cvt_pk_bf16_f32 v252, v238, v239
	v_cvt_pk_bf16_f32 v253, v250, v251
	v_pk_mul_f32 v[238:239], v[82:83], v[230:231]
	v_pk_mul_f32 v[250:251], v[84:85], v[232:233]
	v_cvt_pk_bf16_f32 v254, v238, v239
	v_cvt_pk_bf16_f32 v255, v250, v251
	s_nop 1
	v_permlane16_swap_b32_e32 v252, v254
	v_permlane16_swap_b32_e32 v253, v255
	global_store_dwordx4 v[234:235], v[252:255], off offset:64
	v_pk_mul_f32 v[210:211], v[94:95], v[94:95]
	v_pk_fma_f32 v[210:211], v[96:97], v[96:97], v[210:211]
	v_pk_fma_f32 v[210:211], v[90:91], v[90:91], v[210:211]
	v_pk_fma_f32 v[210:211], v[92:93], v[92:93], v[210:211]
	v_pk_fma_f32 v[210:211], v[86:87], v[86:87], v[210:211]
	v_pk_fma_f32 v[210:211], v[88:89], v[88:89], v[210:211]
	v_pk_fma_f32 v[210:211], v[82:83], v[82:83], v[210:211]
	v_pk_fma_f32 v[210:211], v[84:85], v[84:85], v[210:211]
	v_add_f32_e32 v212, v210, v211
	v_mov_b32_e32 v213, v212
	v_mov_b32_e32 v214, v212
	s_nop 1
	v_permlane32_swap_b32_e32 v213, v214
	v_add_f32_e32 v212, v213, v214
	v_mov_b32_e32 v213, v212
	v_mov_b32_e32 v214, v212
	s_nop 1
	v_permlane16_swap_b32_e32 v213, v214
	v_add_f32_e32 v212, v213, v214
	s_mov_b64 exec, 0xffff
	global_store_dword v[236:237], v212, off
	s_mov_b64 exec, -1
	v_add_co_u32_e32 v234, vcc, 0x8000, v234
	s_nop 1
	v_addc_co_u32_e32 v235, vcc, 0, v235, vcc
	v_add_co_u32_e32 v236, vcc, 0x400, v236
	s_nop 1
	v_addc_co_u32_e32 v237, vcc, 0, v237, vcc
	global_load_dwordx4 v[130:133], v[246:247], off
	global_load_dwordx4 v[134:137], v[246:247], off offset:64
	global_load_dwordx4 v[138:141], v[246:247], off offset:128
	global_load_dwordx4 v[142:145], v[246:247], off offset:192
	v_add_co_u32_e32 v246, vcc, 0x10000, v246
	s_nop 1
	v_addc_co_u32_e32 v247, vcc, 0, v247, vcc
	global_load_dwordx4 v[94:97], v[246:247], off
	global_load_dwordx4 v[90:93], v[246:247], off offset:64
	global_load_dwordx4 v[86:89], v[246:247], off offset:128
	global_load_dwordx4 v[82:85], v[246:247], off offset:192
	s_waitcnt vmcnt(30)
	v_pk_add_f32 v[78:79], v[78:79], v[126:127]
	v_pk_add_f32 v[80:81], v[80:81], v[128:129]
	v_pk_add_f32 v[74:75], v[74:75], v[122:123]
	v_pk_add_f32 v[76:77], v[76:77], v[124:125]
	v_pk_add_f32 v[70:71], v[70:71], v[118:119]
	v_pk_add_f32 v[72:73], v[72:73], v[120:121]
	v_pk_add_f32 v[66:67], v[66:67], v[114:115]
	v_pk_add_f32 v[68:69], v[68:69], v[116:117]
	global_store_dwordx4 v[248:249], v[78:81], off
	global_store_dwordx4 v[248:249], v[74:77], off offset:64
	global_store_dwordx4 v[248:249], v[70:73], off offset:128
	global_store_dwordx4 v[248:249], v[66:69], off offset:192
	v_add_co_u32_e32 v248, vcc, 0x10000, v248
	s_nop 1
	v_addc_co_u32_e32 v249, vcc, 0, v249, vcc
	v_pk_mul_f32 v[238:239], v[78:79], v[218:219]
	v_pk_mul_f32 v[250:251], v[80:81], v[220:221]
	v_cvt_pk_bf16_f32 v252, v238, v239
	v_cvt_pk_bf16_f32 v253, v250, v251
	v_pk_mul_f32 v[238:239], v[74:75], v[222:223]
	v_pk_mul_f32 v[250:251], v[76:77], v[224:225]
	v_cvt_pk_bf16_f32 v254, v238, v239
	v_cvt_pk_bf16_f32 v255, v250, v251
	s_nop 1
	v_permlane16_swap_b32_e32 v252, v254
	v_permlane16_swap_b32_e32 v253, v255
	global_store_dwordx4 v[234:235], v[252:255], off
	v_pk_mul_f32 v[238:239], v[70:71], v[226:227]
	v_pk_mul_f32 v[250:251], v[72:73], v[228:229]
	v_cvt_pk_bf16_f32 v252, v238, v239
	v_cvt_pk_bf16_f32 v253, v250, v251
	v_pk_mul_f32 v[238:239], v[66:67], v[230:231]
	v_pk_mul_f32 v[250:251], v[68:69], v[232:233]
	v_cvt_pk_bf16_f32 v254, v238, v239
	v_cvt_pk_bf16_f32 v255, v250, v251
	s_nop 1
	v_permlane16_swap_b32_e32 v252, v254
	v_permlane16_swap_b32_e32 v253, v255
	global_store_dwordx4 v[234:235], v[252:255], off offset:64
	v_pk_mul_f32 v[210:211], v[78:79], v[78:79]
	v_pk_fma_f32 v[210:211], v[80:81], v[80:81], v[210:211]
	v_pk_fma_f32 v[210:211], v[74:75], v[74:75], v[210:211]
	v_pk_fma_f32 v[210:211], v[76:77], v[76:77], v[210:211]
	v_pk_fma_f32 v[210:211], v[70:71], v[70:71], v[210:211]
	v_pk_fma_f32 v[210:211], v[72:73], v[72:73], v[210:211]
	v_pk_fma_f32 v[210:211], v[66:67], v[66:67], v[210:211]
	v_pk_fma_f32 v[210:211], v[68:69], v[68:69], v[210:211]
	v_add_f32_e32 v212, v210, v211
	v_mov_b32_e32 v213, v212
	v_mov_b32_e32 v214, v212
	s_nop 1
	v_permlane32_swap_b32_e32 v213, v214
	v_add_f32_e32 v212, v213, v214
	v_mov_b32_e32 v213, v212
	v_mov_b32_e32 v214, v212
	s_nop 1
	v_permlane16_swap_b32_e32 v213, v214
	v_add_f32_e32 v212, v213, v214
	s_mov_b64 exec, 0xffff
	global_store_dword v[236:237], v212, off
	s_mov_b64 exec, -1
	v_add_co_u32_e32 v234, vcc, 0x8000, v234
	s_nop 1
	v_addc_co_u32_e32 v235, vcc, 0, v235, vcc
	v_add_co_u32_e32 v236, vcc, 0x400, v236
	s_nop 1
	v_addc_co_u32_e32 v237, vcc, 0, v237, vcc
	s_waitcnt vmcnt(26)
	v_pk_add_f32 v[60:61], v[60:61], v[146:147]
	v_pk_add_f32 v[62:63], v[62:63], v[148:149]
	v_pk_add_f32 v[56:57], v[56:57], v[150:151]
	v_pk_add_f32 v[58:59], v[58:59], v[152:153]
	v_pk_add_f32 v[52:53], v[52:53], v[202:203]
	v_pk_add_f32 v[54:55], v[54:55], v[204:205]
	v_pk_add_f32 v[48:49], v[48:49], v[206:207]
	v_pk_add_f32 v[50:51], v[50:51], v[208:209]
	global_store_dwordx4 v[248:249], v[60:63], off
	global_store_dwordx4 v[248:249], v[56:59], off offset:64
	global_store_dwordx4 v[248:249], v[52:55], off offset:128
	global_store_dwordx4 v[248:249], v[48:51], off offset:192
	v_add_co_u32_e32 v248, vcc, 0x10000, v248
	s_nop 1
	v_addc_co_u32_e32 v249, vcc, 0, v249, vcc
	v_pk_mul_f32 v[238:239], v[60:61], v[218:219]
	v_pk_mul_f32 v[250:251], v[62:63], v[220:221]
	v_cvt_pk_bf16_f32 v252, v238, v239
	v_cvt_pk_bf16_f32 v253, v250, v251
	v_pk_mul_f32 v[238:239], v[56:57], v[222:223]
	v_pk_mul_f32 v[250:251], v[58:59], v[224:225]
	v_cvt_pk_bf16_f32 v254, v238, v239
	v_cvt_pk_bf16_f32 v255, v250, v251
	s_nop 1
	v_permlane16_swap_b32_e32 v252, v254
	v_permlane16_swap_b32_e32 v253, v255
	global_store_dwordx4 v[234:235], v[252:255], off
	v_pk_mul_f32 v[238:239], v[52:53], v[226:227]
	v_pk_mul_f32 v[250:251], v[54:55], v[228:229]
	v_cvt_pk_bf16_f32 v252, v238, v239
	v_cvt_pk_bf16_f32 v253, v250, v251
	v_pk_mul_f32 v[238:239], v[48:49], v[230:231]
	v_pk_mul_f32 v[250:251], v[50:51], v[232:233]
	v_cvt_pk_bf16_f32 v254, v238, v239
	v_cvt_pk_bf16_f32 v255, v250, v251
	s_nop 1
	v_permlane16_swap_b32_e32 v252, v254
	v_permlane16_swap_b32_e32 v253, v255
	global_store_dwordx4 v[234:235], v[252:255], off offset:64
	v_pk_mul_f32 v[210:211], v[60:61], v[60:61]
	v_pk_fma_f32 v[210:211], v[62:63], v[62:63], v[210:211]
	v_pk_fma_f32 v[210:211], v[56:57], v[56:57], v[210:211]
	v_pk_fma_f32 v[210:211], v[58:59], v[58:59], v[210:211]
	v_pk_fma_f32 v[210:211], v[52:53], v[52:53], v[210:211]
	v_pk_fma_f32 v[210:211], v[54:55], v[54:55], v[210:211]
	v_pk_fma_f32 v[210:211], v[48:49], v[48:49], v[210:211]
	v_pk_fma_f32 v[210:211], v[50:51], v[50:51], v[210:211]
	v_add_f32_e32 v212, v210, v211
	v_mov_b32_e32 v213, v212
	v_mov_b32_e32 v214, v212
	s_nop 1
	v_permlane32_swap_b32_e32 v213, v214
	v_add_f32_e32 v212, v213, v214
	v_mov_b32_e32 v213, v212
	v_mov_b32_e32 v214, v212
	s_nop 1
	v_permlane16_swap_b32_e32 v213, v214
	v_add_f32_e32 v212, v213, v214
	s_mov_b64 exec, 0xffff
	global_store_dword v[236:237], v212, off
	s_mov_b64 exec, -1
	v_add_co_u32_e32 v234, vcc, 0x8000, v234
	s_nop 1
	v_addc_co_u32_e32 v235, vcc, 0, v235, vcc
	v_add_co_u32_e32 v236, vcc, 0x400, v236
	s_nop 1
	v_addc_co_u32_e32 v237, vcc, 0, v237, vcc
	s_waitcnt vmcnt(29)
	v_pk_add_f32 v[44:45], v[44:45], v[110:111]
	v_pk_add_f32 v[46:47], v[46:47], v[112:113]
	v_pk_add_f32 v[40:41], v[40:41], v[106:107]
	v_pk_add_f32 v[42:43], v[42:43], v[108:109]
	v_pk_add_f32 v[36:37], v[36:37], v[102:103]
	v_pk_add_f32 v[38:39], v[38:39], v[104:105]
	v_pk_add_f32 v[32:33], v[32:33], v[98:99]
	v_pk_add_f32 v[34:35], v[34:35], v[100:101]
	global_store_dwordx4 v[248:249], v[44:47], off
	global_store_dwordx4 v[248:249], v[40:43], off offset:64
	global_store_dwordx4 v[248:249], v[36:39], off offset:128
	global_store_dwordx4 v[248:249], v[32:35], off offset:192
	v_add_co_u32_e32 v248, vcc, 0x10000, v248
	s_nop 1
	v_addc_co_u32_e32 v249, vcc, 0, v249, vcc
	v_pk_mul_f32 v[238:239], v[44:45], v[218:219]
	v_pk_mul_f32 v[250:251], v[46:47], v[220:221]
	v_cvt_pk_bf16_f32 v252, v238, v239
	v_cvt_pk_bf16_f32 v253, v250, v251
	v_pk_mul_f32 v[238:239], v[40:41], v[222:223]
	v_pk_mul_f32 v[250:251], v[42:43], v[224:225]
	v_cvt_pk_bf16_f32 v254, v238, v239
	v_cvt_pk_bf16_f32 v255, v250, v251
	s_nop 1
	v_permlane16_swap_b32_e32 v252, v254
	v_permlane16_swap_b32_e32 v253, v255
	global_store_dwordx4 v[234:235], v[252:255], off
	v_pk_mul_f32 v[238:239], v[36:37], v[226:227]
	v_pk_mul_f32 v[250:251], v[38:39], v[228:229]
	v_cvt_pk_bf16_f32 v252, v238, v239
	v_cvt_pk_bf16_f32 v253, v250, v251
	v_pk_mul_f32 v[238:239], v[32:33], v[230:231]
	v_pk_mul_f32 v[250:251], v[34:35], v[232:233]
	v_cvt_pk_bf16_f32 v254, v238, v239
	v_cvt_pk_bf16_f32 v255, v250, v251
	s_nop 1
	v_permlane16_swap_b32_e32 v252, v254
	v_permlane16_swap_b32_e32 v253, v255
	global_store_dwordx4 v[234:235], v[252:255], off offset:64
	v_pk_mul_f32 v[210:211], v[44:45], v[44:45]
	v_pk_fma_f32 v[210:211], v[46:47], v[46:47], v[210:211]
	v_pk_fma_f32 v[210:211], v[40:41], v[40:41], v[210:211]
	v_pk_fma_f32 v[210:211], v[42:43], v[42:43], v[210:211]
	v_pk_fma_f32 v[210:211], v[36:37], v[36:37], v[210:211]
	v_pk_fma_f32 v[210:211], v[38:39], v[38:39], v[210:211]
	v_pk_fma_f32 v[210:211], v[32:33], v[32:33], v[210:211]
	v_pk_fma_f32 v[210:211], v[34:35], v[34:35], v[210:211]
	v_add_f32_e32 v212, v210, v211
	v_mov_b32_e32 v213, v212
	v_mov_b32_e32 v214, v212
	s_nop 1
	v_permlane32_swap_b32_e32 v213, v214
	v_add_f32_e32 v212, v213, v214
	v_mov_b32_e32 v213, v212
	v_mov_b32_e32 v214, v212
	s_nop 1
	v_permlane16_swap_b32_e32 v213, v214
	v_add_f32_e32 v212, v213, v214
	s_mov_b64 exec, 0xffff
	global_store_dword v[236:237], v212, off
	s_mov_b64 exec, -1
	v_add_co_u32_e32 v234, vcc, 0x8000, v234
	s_nop 1
	v_addc_co_u32_e32 v235, vcc, 0, v235, vcc
	v_add_co_u32_e32 v236, vcc, 0x400, v236
	s_nop 1
	v_addc_co_u32_e32 v237, vcc, 0, v237, vcc
	s_waitcnt vmcnt(25)
	v_pk_add_f32 v[28:29], v[28:29], v[130:131]
	v_pk_add_f32 v[30:31], v[30:31], v[132:133]
	v_pk_add_f32 v[24:25], v[24:25], v[134:135]
	v_pk_add_f32 v[26:27], v[26:27], v[136:137]
	v_pk_add_f32 v[20:21], v[20:21], v[138:139]
	v_pk_add_f32 v[22:23], v[22:23], v[140:141]
	v_pk_add_f32 v[16:17], v[16:17], v[142:143]
	v_pk_add_f32 v[18:19], v[18:19], v[144:145]
	global_store_dwordx4 v[248:249], v[28:31], off
	global_store_dwordx4 v[248:249], v[24:27], off offset:64
	global_store_dwordx4 v[248:249], v[20:23], off offset:128
	global_store_dwordx4 v[248:249], v[16:19], off offset:192
	v_add_co_u32_e32 v248, vcc, 0x10000, v248
	s_nop 1
	v_addc_co_u32_e32 v249, vcc, 0, v249, vcc
	v_pk_mul_f32 v[238:239], v[28:29], v[218:219]
	v_pk_mul_f32 v[250:251], v[30:31], v[220:221]
	v_cvt_pk_bf16_f32 v252, v238, v239
	v_cvt_pk_bf16_f32 v253, v250, v251
	v_pk_mul_f32 v[238:239], v[24:25], v[222:223]
	v_pk_mul_f32 v[250:251], v[26:27], v[224:225]
	v_cvt_pk_bf16_f32 v254, v238, v239
	v_cvt_pk_bf16_f32 v255, v250, v251
	s_nop 1
	v_permlane16_swap_b32_e32 v252, v254
	v_permlane16_swap_b32_e32 v253, v255
	global_store_dwordx4 v[234:235], v[252:255], off
	v_pk_mul_f32 v[238:239], v[20:21], v[226:227]
	v_pk_mul_f32 v[250:251], v[22:23], v[228:229]
	v_cvt_pk_bf16_f32 v252, v238, v239
	v_cvt_pk_bf16_f32 v253, v250, v251
	v_pk_mul_f32 v[238:239], v[16:17], v[230:231]
	v_pk_mul_f32 v[250:251], v[18:19], v[232:233]
	v_cvt_pk_bf16_f32 v254, v238, v239
	v_cvt_pk_bf16_f32 v255, v250, v251
	s_nop 1
	v_permlane16_swap_b32_e32 v252, v254
	v_permlane16_swap_b32_e32 v253, v255
	global_store_dwordx4 v[234:235], v[252:255], off offset:64
	v_pk_mul_f32 v[210:211], v[28:29], v[28:29]
	v_pk_fma_f32 v[210:211], v[30:31], v[30:31], v[210:211]
	v_pk_fma_f32 v[210:211], v[24:25], v[24:25], v[210:211]
	v_pk_fma_f32 v[210:211], v[26:27], v[26:27], v[210:211]
	v_pk_fma_f32 v[210:211], v[20:21], v[20:21], v[210:211]
	v_pk_fma_f32 v[210:211], v[22:23], v[22:23], v[210:211]
	v_pk_fma_f32 v[210:211], v[16:17], v[16:17], v[210:211]
	v_pk_fma_f32 v[210:211], v[18:19], v[18:19], v[210:211]
	v_add_f32_e32 v212, v210, v211
	v_mov_b32_e32 v213, v212
	v_mov_b32_e32 v214, v212
	s_nop 1
	v_permlane32_swap_b32_e32 v213, v214
	v_add_f32_e32 v212, v213, v214
	v_mov_b32_e32 v213, v212
	v_mov_b32_e32 v214, v212
	s_nop 1
	v_permlane16_swap_b32_e32 v213, v214
	v_add_f32_e32 v212, v213, v214
	s_mov_b64 exec, 0xffff
	global_store_dword v[236:237], v212, off
	s_mov_b64 exec, -1
	v_add_co_u32_e32 v234, vcc, 0x8000, v234
	s_nop 1
	v_addc_co_u32_e32 v235, vcc, 0, v235, vcc
	v_add_co_u32_e32 v236, vcc, 0x400, v236
	s_nop 1
	v_addc_co_u32_e32 v237, vcc, 0, v237, vcc
	s_waitcnt vmcnt(28)
	v_pk_add_f32 v[12:13], v[12:13], v[94:95]
	v_pk_add_f32 v[14:15], v[14:15], v[96:97]
	v_pk_add_f32 v[8:9], v[8:9], v[90:91]
	v_pk_add_f32 v[10:11], v[10:11], v[92:93]
	v_pk_add_f32 v[4:5], v[4:5], v[86:87]
	v_pk_add_f32 v[6:7], v[6:7], v[88:89]
	v_pk_add_f32 v[0:1], v[0:1], v[82:83]
	v_pk_add_f32 v[2:3], v[2:3], v[84:85]
	global_store_dwordx4 v[248:249], v[12:15], off
	global_store_dwordx4 v[248:249], v[8:11], off offset:64
	global_store_dwordx4 v[248:249], v[4:7], off offset:128
	global_store_dwordx4 v[248:249], v[0:3], off offset:192
	v_pk_mul_f32 v[238:239], v[12:13], v[218:219]
	v_pk_mul_f32 v[250:251], v[14:15], v[220:221]
	v_cvt_pk_bf16_f32 v252, v238, v239
	v_cvt_pk_bf16_f32 v253, v250, v251
	v_pk_mul_f32 v[238:239], v[8:9], v[222:223]
	v_pk_mul_f32 v[250:251], v[10:11], v[224:225]
	v_cvt_pk_bf16_f32 v254, v238, v239
	v_cvt_pk_bf16_f32 v255, v250, v251
	s_nop 1
	v_permlane16_swap_b32_e32 v252, v254
	v_permlane16_swap_b32_e32 v253, v255
	global_store_dwordx4 v[234:235], v[252:255], off
	v_pk_mul_f32 v[238:239], v[4:5], v[226:227]
	v_pk_mul_f32 v[250:251], v[6:7], v[228:229]
	v_cvt_pk_bf16_f32 v252, v238, v239
	v_cvt_pk_bf16_f32 v253, v250, v251
	v_pk_mul_f32 v[238:239], v[0:1], v[230:231]
	v_pk_mul_f32 v[250:251], v[2:3], v[232:233]
	v_cvt_pk_bf16_f32 v254, v238, v239
	v_cvt_pk_bf16_f32 v255, v250, v251
	s_nop 1
	v_permlane16_swap_b32_e32 v252, v254
	v_permlane16_swap_b32_e32 v253, v255
	global_store_dwordx4 v[234:235], v[252:255], off offset:64
	v_pk_mul_f32 v[210:211], v[12:13], v[12:13]
	v_pk_fma_f32 v[210:211], v[14:15], v[14:15], v[210:211]
	v_pk_fma_f32 v[210:211], v[8:9], v[8:9], v[210:211]
	v_pk_fma_f32 v[210:211], v[10:11], v[10:11], v[210:211]
	v_pk_fma_f32 v[210:211], v[4:5], v[4:5], v[210:211]
	v_pk_fma_f32 v[210:211], v[6:7], v[6:7], v[210:211]
	v_pk_fma_f32 v[210:211], v[0:1], v[0:1], v[210:211]
	v_pk_fma_f32 v[210:211], v[2:3], v[2:3], v[210:211]
	v_add_f32_e32 v212, v210, v211
	v_mov_b32_e32 v213, v212
	v_mov_b32_e32 v214, v212
	s_nop 1
	v_permlane32_swap_b32_e32 v213, v214
	v_add_f32_e32 v212, v213, v214
	v_mov_b32_e32 v213, v212
	v_mov_b32_e32 v214, v212
	s_nop 1
	v_permlane16_swap_b32_e32 v213, v214
	v_add_f32_e32 v212, v213, v214
	s_mov_b64 exec, 0xffff
	global_store_dword v[236:237], v212, off
	s_mov_b64 exec, -1
	s_andn2_b64 vcc, exec, s[28:29]
	s_cbranch_vccz .LBB0_1524

.LBB0_1578:
	s_or_b64 exec, exec, s[0:1]
	s_branch .LBB0_1634
	v_mov_b32_e32 v0, v166
	s_barrier
	v_readlane_b32 s0, v244, 3
	v_ashrrev_i32_e32 v1, 6, v0
	s_nop 0
	v_add_u32_e32 v24, s0, v1
	s_movk_i32 s0, 0x4000
	v_cmp_gt_i32_e32 vcc, s0, v24
	s_and_saveexec_b64 s[24:25], vcc
	s_cbranch_execz .LBB0_1581
	v_and_b32_e32 v16, 63, v0
	v_readlane_b32 s0, v241, 46
	v_lshlrev_b32_e32 v64, 4, v16
	v_readlane_b32 s1, v241, 47
	s_nop 4
	global_load_dwordx4 v[0:3], v64, s[0:1]
	global_load_dwordx4 v[4:7], v64, s[0:1] offset:1024
	global_load_dwordx4 v[8:11], v64, s[0:1] offset:2048
	global_load_dwordx4 v[12:15], v64, s[0:1] offset:3072
	v_cmp_lt_i32_e32 vcc, v157, v168
	v_lshlrev_b32_e32 v16, 2, v16
	v_or_b32_e32 v18, 0x100, v16
	v_cndmask_b32_e32 v17, v155, v157, vcc
	v_cmp_lt_i32_e32 vcc, v169, v168
	s_waitcnt vmcnt(26)
	v_lshlrev_b32_e32 v37, 2, v17
	v_or_b32_e32 v20, 0x200, v16
	v_cndmask_b32_e32 v17, v155, v169, vcc
	v_or_b32_e32 v22, 0x300, v16
	v_lshlrev_b32_e32 v38, 2, v17
	v_lshl_add_u64 v[26:27], s[38:39], 0, v[64:65]
	s_mov_b64 s[28:29], 0
	v_lshlrev_b32_e32 v64, 1, v16
	v_lshlrev_b32_e32 v28, 1, v18
	v_lshlrev_b32_e32 v30, 1, v20
	v_lshlrev_b32_e32 v32, 1, v22

.LBB0_1636:
	s_add_i32 s64, s64, 1
	s_mul_hi_i32 s1, s24, 0x2c0000
	s_mul_i32 s24, s24, 0x2c0000
	s_add_u32 s24, s18, s24
	s_addc_u32 s25, s19, s1
	s_lshl_b32 s0, s0, 8
	s_ashr_i32 s1, s0, 31
	s_lshl_b64 s[0:1], s[0:1], 1
	s_add_u32 s0, s24, s0
	s_mov_b32 s24, 0x7fff80
	s_addc_u32 s1, s25, s1
	v_mov_b32_e32 v248, v166
	v_and_b32_e32 v249, 15, v248
	v_lshrrev_b32_e32 v250, 1, v248
	v_and_b32_e32 v251, 0xc0, v248
	v_and_or_b32 v249, v250, s24, v249
	v_and_b32_e32 v250, 16, v248
	v_lshrrev_b32_e32 v248, 2, v248
	v_and_b32_e32 v248, 8, v248
	v_or_b32_e32 v248, v248, v250
	v_mul_u32_u24_e32 v250, 0x1600, v249
	v_or3_b32 v248, v248, v251, v250
	v_mov_b32_e32 v249, 0
	v_lshl_add_u64 v[246:247], v[248:249], 1, s[0:1]
	v_mov_b32_e32 v130, 0x3a800000
	s_cmp_eq_u32 s26, 0
	s_cbranch_scc0 .Lf3_nopre
	s_waitcnt vmcnt(23)
	s_branch .Lf3_j
.Lf3_nopre:
	s_waitcnt vmcnt(7)
.Lf3_j:
	v_add_f32_e32 v132, v210, v211
	v_add_f32_e32 v133, v212, v213
	v_add_f32_e32 v132, v132, v133
	v_mov_b32_e32 v133, v132
	v_mov_b32_e32 v134, v132
	s_nop 1
	v_permlane32_swap_b32_e32 v133, v134
	v_add_f32_e32 v132, v133, v134
	v_mov_b32_e32 v133, v132
	v_mov_b32_e32 v134, v132
	s_nop 1
	v_permlane16_swap_b32_e32 v133, v134
	v_add_f32_e32 v132, v133, v134
	v_fmaak_f32 v133, v132, v130, 0x3727c5ac
	v_rsq_f32_e32 v134, v133
	v_mul_f32_e32 v133, 0.5, v133
	s_nop 0
	v_mul_f32_e32 v132, v133, v134
	v_fma_f32 v132, -v132, v134, 0.5
	v_fma_f32 v136, v134, v132, v134
	v_mov_b32_e32 v137, v136
	v_pk_mul_f32 v[126:127], v[126:127], v[136:137]
	v_pk_mul_f32 v[128:129], v[128:129], v[136:137]
	v_pk_mul_f32 v[122:123], v[122:123], v[136:137]
	v_pk_mul_f32 v[124:125], v[124:125], v[136:137]
	v_pk_mul_f32 v[118:119], v[118:119], v[136:137]
	v_pk_mul_f32 v[120:121], v[120:121], v[136:137]
	v_pk_mul_f32 v[114:115], v[114:115], v[136:137]
	v_pk_mul_f32 v[116:117], v[116:117], v[136:137]
	v_cvt_pk_bf16_f32 v126, v126, v127
	v_cvt_pk_bf16_f32 v127, v128, v129
	v_cvt_pk_bf16_f32 v128, v122, v123
	v_cvt_pk_bf16_f32 v129, v124, v125
	v_cvt_pk_bf16_f32 v118, v118, v119
	v_cvt_pk_bf16_f32 v119, v120, v121
	v_cvt_pk_bf16_f32 v120, v114, v115
	v_cvt_pk_bf16_f32 v121, v116, v117
	s_nop 1
	v_permlane16_swap_b32_e32 v126, v128
	v_permlane16_swap_b32_e32 v127, v129
	v_permlane16_swap_b32_e32 v118, v120
	v_permlane16_swap_b32_e32 v119, v121
	global_store_dwordx4 v[246:247], v[126:129], off
	global_store_dwordx4 v[246:247], v[118:121], off offset:64
	v_add_co_u32_e32 v246, vcc, 0x2c000, v246
	s_nop 1
	v_addc_co_u32_e32 v247, vcc, 0, v247, vcc
	s_waitcnt vmcnt(8)
	v_add_f32_e32 v132, v214, v215
	v_add_f32_e32 v133, v216, v217
	v_add_f32_e32 v132, v132, v133
	v_mov_b32_e32 v133, v132
	v_mov_b32_e32 v134, v132
	s_nop 1
	v_permlane32_swap_b32_e32 v133, v134
	v_add_f32_e32 v132, v133, v134
	v_mov_b32_e32 v133, v132
	v_mov_b32_e32 v134, v132
	s_nop 1
	v_permlane16_swap_b32_e32 v133, v134
	v_add_f32_e32 v132, v133, v134
	v_fmaak_f32 v133, v132, v130, 0x3727c5ac
	v_rsq_f32_e32 v134, v133
	v_mul_f32_e32 v133, 0.5, v133
	s_nop 0
	v_mul_f32_e32 v132, v133, v134
	v_fma_f32 v132, -v132, v134, 0.5
	v_fma_f32 v136, v134, v132, v134
	v_mov_b32_e32 v137, v136
	v_pk_mul_f32 v[110:111], v[110:111], v[136:137]
	v_pk_mul_f32 v[112:113], v[112:113], v[136:137]
	v_pk_mul_f32 v[106:107], v[106:107], v[136:137]
	v_pk_mul_f32 v[108:109], v[108:109], v[136:137]
	v_pk_mul_f32 v[102:103], v[102:103], v[136:137]
	v_pk_mul_f32 v[104:105], v[104:105], v[136:137]
	v_pk_mul_f32 v[98:99], v[98:99], v[136:137]
	v_pk_mul_f32 v[100:101], v[100:101], v[136:137]
	v_cvt_pk_bf16_f32 v110, v110, v111
	v_cvt_pk_bf16_f32 v111, v112, v113
	v_cvt_pk_bf16_f32 v112, v106, v107
	v_cvt_pk_bf16_f32 v113, v108, v109
	v_cvt_pk_bf16_f32 v102, v102, v103
	v_cvt_pk_bf16_f32 v103, v104, v105
	v_cvt_pk_bf16_f32 v104, v98, v99
	v_cvt_pk_bf16_f32 v105, v100, v101
	s_nop 1
	v_permlane16_swap_b32_e32 v110, v112
	v_permlane16_swap_b32_e32 v111, v113
	v_permlane16_swap_b32_e32 v102, v104
	v_permlane16_swap_b32_e32 v103, v105
	global_store_dwordx4 v[246:247], v[110:113], off
	global_store_dwordx4 v[246:247], v[102:105], off offset:64
	v_add_co_u32_e32 v246, vcc, 0x2c000, v246
	s_nop 1
	v_addc_co_u32_e32 v247, vcc, 0, v247, vcc
	s_waitcnt vmcnt(9)
	v_add_f32_e32 v132, v218, v219
	v_add_f32_e32 v133, v220, v221
	v_add_f32_e32 v132, v132, v133
	v_mov_b32_e32 v133, v132
	v_mov_b32_e32 v134, v132
	s_nop 1
	v_permlane32_swap_b32_e32 v133, v134
	v_add_f32_e32 v132, v133, v134
	v_mov_b32_e32 v133, v132
	v_mov_b32_e32 v134, v132
	s_nop 1
	v_permlane16_swap_b32_e32 v133, v134
	v_add_f32_e32 v132, v133, v134
	v_fmaak_f32 v133, v132, v130, 0x3727c5ac
	v_rsq_f32_e32 v134, v133
	v_mul_f32_e32 v133, 0.5, v133
	s_nop 0
	v_mul_f32_e32 v132, v133, v134
	v_fma_f32 v132, -v132, v134, 0.5
	v_fma_f32 v136, v134, v132, v134
	v_mov_b32_e32 v137, v136
	v_pk_mul_f32 v[94:95], v[94:95], v[136:137]
	v_pk_mul_f32 v[96:97], v[96:97], v[136:137]
	v_pk_mul_f32 v[90:91], v[90:91], v[136:137]
	v_pk_mul_f32 v[92:93], v[92:93], v[136:137]
	v_pk_mul_f32 v[86:87], v[86:87], v[136:137]
	v_pk_mul_f32 v[88:89], v[88:89], v[136:137]
	v_pk_mul_f32 v[82:83], v[82:83], v[136:137]
	v_pk_mul_f32 v[84:85], v[84:85], v[136:137]
	v_cvt_pk_bf16_f32 v94, v94, v95
	v_cvt_pk_bf16_f32 v95, v96, v97
	v_cvt_pk_bf16_f32 v96, v90, v91
	v_cvt_pk_bf16_f32 v97, v92, v93
	v_cvt_pk_bf16_f32 v86, v86, v87
	v_cvt_pk_bf16_f32 v87, v88, v89
	v_cvt_pk_bf16_f32 v88, v82, v83
	v_cvt_pk_bf16_f32 v89, v84, v85
	s_nop 1
	v_permlane16_swap_b32_e32 v94, v96
	v_permlane16_swap_b32_e32 v95, v97
	v_permlane16_swap_b32_e32 v86, v88
	v_permlane16_swap_b32_e32 v87, v89
	global_store_dwordx4 v[246:247], v[94:97], off
	global_store_dwordx4 v[246:247], v[86:89], off offset:64
	v_add_co_u32_e32 v246, vcc, 0x2c000, v246
	s_nop 1
	v_addc_co_u32_e32 v247, vcc, 0, v247, vcc
	s_waitcnt vmcnt(10)
	v_add_f32_e32 v132, v222, v223
	v_add_f32_e32 v133, v224, v225
	v_add_f32_e32 v132, v132, v133
	v_mov_b32_e32 v133, v132
	v_mov_b32_e32 v134, v132
	s_nop 1
	v_permlane32_swap_b32_e32 v133, v134
	v_add_f32_e32 v132, v133, v134
	v_mov_b32_e32 v133, v132
	v_mov_b32_e32 v134, v132
	s_nop 1
	v_permlane16_swap_b32_e32 v133, v134
	v_add_f32_e32 v132, v133, v134
	v_fmaak_f32 v133, v132, v130, 0x3727c5ac
	v_rsq_f32_e32 v134, v133
	v_mul_f32_e32 v133, 0.5, v133
	s_nop 0
	v_mul_f32_e32 v132, v133, v134
	v_fma_f32 v132, -v132, v134, 0.5
	v_fma_f32 v136, v134, v132, v134
	v_mov_b32_e32 v137, v136
	v_pk_mul_f32 v[78:79], v[78:79], v[136:137]
	v_pk_mul_f32 v[80:81], v[80:81], v[136:137]
	v_pk_mul_f32 v[74:75], v[74:75], v[136:137]
	v_pk_mul_f32 v[76:77], v[76:77], v[136:137]
	v_pk_mul_f32 v[70:71], v[70:71], v[136:137]
	v_pk_mul_f32 v[72:73], v[72:73], v[136:137]
	v_pk_mul_f32 v[66:67], v[66:67], v[136:137]
	v_pk_mul_f32 v[68:69], v[68:69], v[136:137]
	v_cvt_pk_bf16_f32 v78, v78, v79
	v_cvt_pk_bf16_f32 v79, v80, v81
	v_cvt_pk_bf16_f32 v80, v74, v75
	v_cvt_pk_bf16_f32 v81, v76, v77
	v_cvt_pk_bf16_f32 v70, v70, v71
	v_cvt_pk_bf16_f32 v71, v72, v73
	v_cvt_pk_bf16_f32 v72, v66, v67
	v_cvt_pk_bf16_f32 v73, v68, v69
	s_nop 1
	v_permlane16_swap_b32_e32 v78, v80
	v_permlane16_swap_b32_e32 v79, v81
	v_permlane16_swap_b32_e32 v70, v72
	v_permlane16_swap_b32_e32 v71, v73
	global_store_dwordx4 v[246:247], v[78:81], off
	global_store_dwordx4 v[246:247], v[70:73], off offset:64
	v_add_co_u32_e32 v246, vcc, 0x2c000, v246
	s_nop 1
	v_addc_co_u32_e32 v247, vcc, 0, v247, vcc
	s_waitcnt vmcnt(11)
	v_add_f32_e32 v132, v226, v227
	v_add_f32_e32 v133, v228, v229
	v_add_f32_e32 v132, v132, v133
	v_mov_b32_e32 v133, v132
	v_mov_b32_e32 v134, v132
	s_nop 1
	v_permlane32_swap_b32_e32 v133, v134
	v_add_f32_e32 v132, v133, v134
	v_mov_b32_e32 v133, v132
	v_mov_b32_e32 v134, v132
	s_nop 1
	v_permlane16_swap_b32_e32 v133, v134
	v_add_f32_e32 v132, v133, v134
	v_fmaak_f32 v133, v132, v130, 0x3727c5ac
	v_rsq_f32_e32 v134, v133
	v_mul_f32_e32 v133, 0.5, v133
	s_nop 0
	v_mul_f32_e32 v132, v133, v134
	v_fma_f32 v132, -v132, v134, 0.5
	v_fma_f32 v136, v134, v132, v134
	v_mov_b32_e32 v137, v136
	v_pk_mul_f32 v[60:61], v[60:61], v[136:137]
	v_pk_mul_f32 v[62:63], v[62:63], v[136:137]
	v_pk_mul_f32 v[56:57], v[56:57], v[136:137]
	v_pk_mul_f32 v[58:59], v[58:59], v[136:137]
	v_pk_mul_f32 v[52:53], v[52:53], v[136:137]
	v_pk_mul_f32 v[54:55], v[54:55], v[136:137]
	v_pk_mul_f32 v[48:49], v[48:49], v[136:137]
	v_pk_mul_f32 v[50:51], v[50:51], v[136:137]
	v_cvt_pk_bf16_f32 v60, v60, v61
	v_cvt_pk_bf16_f32 v61, v62, v63
	v_cvt_pk_bf16_f32 v62, v56, v57
	v_cvt_pk_bf16_f32 v63, v58, v59
	v_cvt_pk_bf16_f32 v52, v52, v53
	v_cvt_pk_bf16_f32 v53, v54, v55
	v_cvt_pk_bf16_f32 v54, v48, v49
	v_cvt_pk_bf16_f32 v55, v50, v51
	s_nop 1
	v_permlane16_swap_b32_e32 v60, v62
	v_permlane16_swap_b32_e32 v61, v63
	v_permlane16_swap_b32_e32 v52, v54
	v_permlane16_swap_b32_e32 v53, v55
	global_store_dwordx4 v[246:247], v[60:63], off
	global_store_dwordx4 v[246:247], v[52:55], off offset:64
	v_add_co_u32_e32 v246, vcc, 0x2c000, v246
	s_nop 1
	v_addc_co_u32_e32 v247, vcc, 0, v247, vcc
	s_waitcnt vmcnt(12)
	v_add_f32_e32 v132, v230, v231
	v_add_f32_e32 v133, v232, v233
	v_add_f32_e32 v132, v132, v133
	v_mov_b32_e32 v133, v132
	v_mov_b32_e32 v134, v132
	s_nop 1
	v_permlane32_swap_b32_e32 v133, v134
	v_add_f32_e32 v132, v133, v134
	v_mov_b32_e32 v133, v132
	v_mov_b32_e32 v134, v132
	s_nop 1
	v_permlane16_swap_b32_e32 v133, v134
	v_add_f32_e32 v132, v133, v134
	v_fmaak_f32 v133, v132, v130, 0x3727c5ac
	v_rsq_f32_e32 v134, v133
	v_mul_f32_e32 v133, 0.5, v133
	s_nop 0
	v_mul_f32_e32 v132, v133, v134
	v_fma_f32 v132, -v132, v134, 0.5
	v_fma_f32 v136, v134, v132, v134
	v_mov_b32_e32 v137, v136
	v_pk_mul_f32 v[44:45], v[44:45], v[136:137]
	v_pk_mul_f32 v[46:47], v[46:47], v[136:137]
	v_pk_mul_f32 v[40:41], v[40:41], v[136:137]
	v_pk_mul_f32 v[42:43], v[42:43], v[136:137]
	v_pk_mul_f32 v[36:37], v[36:37], v[136:137]
	v_pk_mul_f32 v[38:39], v[38:39], v[136:137]
	v_pk_mul_f32 v[32:33], v[32:33], v[136:137]
	v_pk_mul_f32 v[34:35], v[34:35], v[136:137]
	v_cvt_pk_bf16_f32 v44, v44, v45
	v_cvt_pk_bf16_f32 v45, v46, v47
	v_cvt_pk_bf16_f32 v46, v40, v41
	v_cvt_pk_bf16_f32 v47, v42, v43
	v_cvt_pk_bf16_f32 v36, v36, v37
	v_cvt_pk_bf16_f32 v37, v38, v39
	v_cvt_pk_bf16_f32 v38, v32, v33
	v_cvt_pk_bf16_f32 v39, v34, v35
	s_nop 1
	v_permlane16_swap_b32_e32 v44, v46
	v_permlane16_swap_b32_e32 v45, v47
	v_permlane16_swap_b32_e32 v36, v38
	v_permlane16_swap_b32_e32 v37, v39
	global_store_dwordx4 v[246:247], v[44:47], off
	global_store_dwordx4 v[246:247], v[36:39], off offset:64
	v_add_co_u32_e32 v246, vcc, 0x2c000, v246
	s_nop 1
	v_addc_co_u32_e32 v247, vcc, 0, v247, vcc
	s_waitcnt vmcnt(13)
	v_add_f32_e32 v132, v234, v235
	v_add_f32_e32 v133, v236, v237
	v_add_f32_e32 v132, v132, v133
	v_mov_b32_e32 v133, v132
	v_mov_b32_e32 v134, v132
	s_nop 1
	v_permlane32_swap_b32_e32 v133, v134
	v_add_f32_e32 v132, v133, v134
	v_mov_b32_e32 v133, v132
	v_mov_b32_e32 v134, v132
	s_nop 1
	v_permlane16_swap_b32_e32 v133, v134
	v_add_f32_e32 v132, v133, v134
	v_fmaak_f32 v133, v132, v130, 0x3727c5ac
	v_rsq_f32_e32 v134, v133
	v_mul_f32_e32 v133, 0.5, v133
	s_nop 0
	v_mul_f32_e32 v132, v133, v134
	v_fma_f32 v132, -v132, v134, 0.5
	v_fma_f32 v136, v134, v132, v134
	v_mov_b32_e32 v137, v136
	v_pk_mul_f32 v[28:29], v[28:29], v[136:137]
	v_pk_mul_f32 v[30:31], v[30:31], v[136:137]
	v_pk_mul_f32 v[24:25], v[24:25], v[136:137]
	v_pk_mul_f32 v[26:27], v[26:27], v[136:137]
	v_pk_mul_f32 v[20:21], v[20:21], v[136:137]
	v_pk_mul_f32 v[22:23], v[22:23], v[136:137]
	v_pk_mul_f32 v[16:17], v[16:17], v[136:137]
	v_pk_mul_f32 v[18:19], v[18:19], v[136:137]
	v_cvt_pk_bf16_f32 v28, v28, v29
	v_cvt_pk_bf16_f32 v29, v30, v31
	v_cvt_pk_bf16_f32 v30, v24, v25
	v_cvt_pk_bf16_f32 v31, v26, v27
	v_cvt_pk_bf16_f32 v20, v20, v21
	v_cvt_pk_bf16_f32 v21, v22, v23
	v_cvt_pk_bf16_f32 v22, v16, v17
	v_cvt_pk_bf16_f32 v23, v18, v19
	s_nop 1
	v_permlane16_swap_b32_e32 v28, v30
	v_permlane16_swap_b32_e32 v29, v31
	v_permlane16_swap_b32_e32 v20, v22
	v_permlane16_swap_b32_e32 v21, v23
	global_store_dwordx4 v[246:247], v[28:31], off
	global_store_dwordx4 v[246:247], v[20:23], off offset:64
	v_add_co_u32_e32 v246, vcc, 0x2c000, v246
	s_nop 1
	v_addc_co_u32_e32 v247, vcc, 0, v247, vcc
	s_waitcnt vmcnt(14)
	v_add_f32_e32 v132, v252, v253
	v_add_f32_e32 v133, v254, v255
	v_add_f32_e32 v132, v132, v133
	v_mov_b32_e32 v133, v132
	v_mov_b32_e32 v134, v132
	s_nop 1
	v_permlane32_swap_b32_e32 v133, v134
	v_add_f32_e32 v132, v133, v134
	v_mov_b32_e32 v133, v132
	v_mov_b32_e32 v134, v132
	s_nop 1
	v_permlane16_swap_b32_e32 v133, v134
	v_add_f32_e32 v132, v133, v134
	v_fmaak_f32 v133, v132, v130, 0x3727c5ac
	v_rsq_f32_e32 v134, v133
	v_mul_f32_e32 v133, 0.5, v133
	s_nop 0
	v_mul_f32_e32 v132, v133, v134
	v_fma_f32 v132, -v132, v134, 0.5
	v_fma_f32 v136, v134, v132, v134
	v_mov_b32_e32 v137, v136
	v_pk_mul_f32 v[12:13], v[12:13], v[136:137]
	v_pk_mul_f32 v[14:15], v[14:15], v[136:137]
	v_pk_mul_f32 v[8:9], v[8:9], v[136:137]
	v_pk_mul_f32 v[10:11], v[10:11], v[136:137]
	v_pk_mul_f32 v[4:5], v[4:5], v[136:137]
	v_pk_mul_f32 v[6:7], v[6:7], v[136:137]
	v_pk_mul_f32 v[0:1], v[0:1], v[136:137]
	v_pk_mul_f32 v[2:3], v[2:3], v[136:137]
	v_cvt_pk_bf16_f32 v12, v12, v13
	v_cvt_pk_bf16_f32 v13, v14, v15
	v_cvt_pk_bf16_f32 v14, v8, v9
	v_cvt_pk_bf16_f32 v15, v10, v11
	v_cvt_pk_bf16_f32 v4, v4, v5
	v_cvt_pk_bf16_f32 v5, v6, v7
	v_cvt_pk_bf16_f32 v6, v0, v1
	v_cvt_pk_bf16_f32 v7, v2, v3
	s_nop 1
	v_permlane16_swap_b32_e32 v12, v14
	v_permlane16_swap_b32_e32 v13, v15
	v_permlane16_swap_b32_e32 v4, v6
	v_permlane16_swap_b32_e32 v5, v7
	global_store_dwordx4 v[246:247], v[12:15], off
	global_store_dwordx4 v[246:247], v[4:7], off offset:64
	s_andn2_b64 vcc, exec, s[26:27]
	s_cbranch_vccz .LBB0_1666

.Lg6_X:
	v_lshrrev_b32_e32 v250, 1, v166
	v_and_b32_e32 v250, 0x80, v250
	v_and_b32_e32 v251, 15, v166
	v_or_b32_e32 v250, v250, v251
	v_lshlrev_b32_e32 v250, 6, v250
	v_and_b32_e32 v251, 0x30, v166
	v_or_b32_e32 v250, v250, v251
	v_lshl_add_u32 v250, s24, 14, v250
	v_mov_b32_e32 v251, 0
	s_add_u32 s26, s92, 0x35624900
	s_addc_u32 s27, s93, 0
	v_lshl_add_u64 v[250:251], v[250:251], 0, s[26:27]
	global_load_dwordx4 v[210:213], v[250:251], off
	global_load_dwordx4 v[214:217], v[250:251], off offset:1024
	global_load_dwordx4 v[218:221], v[250:251], off offset:2048
	global_load_dwordx4 v[222:225], v[250:251], off offset:3072
	v_add_co_u32_e32 v250, vcc, 0x1000, v250
	s_nop 1
	v_addc_co_u32_e32 v251, vcc, 0, v251, vcc
	global_load_dwordx4 v[226:229], v[250:251], off
	global_load_dwordx4 v[230:233], v[250:251], off offset:1024
	global_load_dwordx4 v[234:237], v[250:251], off offset:2048
	global_load_dwordx4 v[252:255], v[250:251], off offset:3072
	s_waitcnt lgkmcnt(0)
	v_mfma_f32_16x16x32_bf16 v[28:31], v[130:133], v[202:205], v[28:31]
	v_mfma_f32_16x16x32_bf16 v[24:27], v[134:137], v[202:205], v[24:27]
	v_mfma_f32_16x16x32_bf16 v[20:23], v[138:141], v[202:205], v[20:23]
	v_mfma_f32_16x16x32_bf16 v[16:19], v[142:145], v[202:205], v[16:19]
	v_mfma_f32_16x16x32_bf16 v[12:15], v[130:133], v[206:209], v[12:15]
	v_mfma_f32_16x16x32_bf16 v[8:11], v[134:137], v[206:209], v[8:11]
	v_mfma_f32_16x16x32_bf16 v[4:7], v[138:141], v[206:209], v[4:7]
	v_mfma_f32_16x16x32_bf16 v[0:3], v[142:145], v[206:209], v[0:3]
	s_nop 7
	s_nop 1
	s_branch .LBB0_1655
